# v8 + sc1 (L1-bypass) on the K-loop LDS-DMA loads
# baseline (speedup 1.0000x reference)
; #define PG8_STAGE(bufoff, gbase, voff) do { _Pragma("unroll") for (int _i = 0; _i < 2; ++_i) \
;         __builtin_amdgcn_global_load_lds((const unsigned*)((const char*)(gbase) + (voff)[_i]), (LAS unsigned*)(lds + (bufoff) + ldsw + _i * 8192), 16, 0, 0); } while (0)
; #define PG8_LDA(dst, b, h) do { _Pragma("unroll") for (int m = 0; m < 4; ++m) _Pragma("unroll") for (int k = 0; k < 2; ++k) dst[m][k] = *(const LAS bf16x8*)(lds + PG8_SA(b, h) + aoff + m * 2048 + k * KOFF); } while (0)
; #define PG8_LDB(dst, b, h) do { _Pragma("unroll") for (int n = 0; n < 2; ++n) _Pragma("unroll") for (int k = 0; k < 2; ++k) dst[n][k] = *(const LAS bf16x8*)(lds + PG8_SB(b, h) + boff + n * 2048 + k * KOFF); } while (0)
; #define PG8_WAIT_V(n) asm volatile("s_waitcnt vmcnt(" #n ")" ::: "memory")
; #define PG8_WAIT_L(n) asm volatile("s_waitcnt lgkmcnt(" #n ")" ::: "memory")
; #define PG8_BAR __builtin_amdgcn_s_barrier()
; #define PG8_SCHED __builtin_amdgcn_sched_barrier(0)
; template <class Epi, bool ALIGN_EPI = true, bool FP8 = false>
; __device__ __forceinline__ void gemm_phase(LAS unsigned char* lds, const Gemm g, const StaticOrder& S, const Epi& E, const int wid) {
;     ...
;             const char* a1 = cA + (size_t)(t + 1) * kstep;
;             const char* a2 = last ? nA : cA + (size_t)(t + 2) * kstep; const char* b2 = last ? nB : cB + (size_t)(t + 2) * kstep;
;             const char* a3 = a2 + kstep; const char* b3 = b2 + kstep;
;             PG8_LDB(B0, 0, 0); PG8_LDB(B1, 0, 1); PG8_SCHED; PG8_LDA(At, 0, 0); PG8_STAGE(PG8_SA(1, 1), a1 + hstep, voffA);
;             PG8_WAIT_V(8); PG8_WAIT_L(0); PG8_BAR; PG8_MMA(0, 0, At, B0); PG8_MMA(0, 1, At, B1); PG8_BAR; PG8_SCHED;
;             PG8_LDA(At, 0, 1); PG8_STAGE(PG8_SB(0, 0), b2, voffB); PG8_STAGE(PG8_SB(0, 1), b2 + hstep, voffB); PG8_STAGE(PG8_SA(0, 0), a2, voffA);
;             PG8_WAIT_V(8); PG8_WAIT_L(0); PG8_BAR; PG8_MMA(1, 0, At, B0); PG8_MMA(1, 1, At, B1); PG8_BAR; PG8_SCHED;
.LBB0_506:
	ds_read_b128 v[146:149], v137
	ds_read_b128 v[154:157], v137 offset:1024
	ds_read_b128 v[158:161], v137 offset:2048
	ds_read_b128 v[162:165], v137 offset:3072
	ds_read_b128 v[166:169], v152
	ds_read_b128 v[170:173], v152 offset:1024
	ds_read_b128 v[174:177], v152 offset:2048
	ds_read_b128 v[178:181], v152 offset:3072
	s_add_i32 s52, s34, 2
	s_add_u32 s35, s30, 0xfff80080
	s_addc_u32 s36, s31, -1
	s_cmp_eq_u32 s39, s34
	s_cselect_b32 s34, s38, s42
	s_cselect_b32 s37, s3, s36
	s_cselect_b32 s36, s23, s35
	s_cselect_b32 s35, s25, s43
	v_lshl_add_u64 v[214:215], s[30:31], 0, v[140:141]
	s_add_i32 m0, s75, 0xc000
	ds_read_b128 v[182:185], v153
	ds_read_b128 v[186:189], v153 offset:1024
	ds_read_b128 v[190:193], v153 offset:2048
	ds_read_b128 v[194:197], v153 offset:3072
	ds_read_b128 v[198:201], v153 offset:4096
	ds_read_b128 v[202:205], v153 offset:5120
	ds_read_b128 v[206:209], v153 offset:6144
	ds_read_b128 v[210:213], v153 offset:7168
	global_load_lds_dwordx4 v[214:215], off sc1
	v_lshl_add_u64 v[214:215], s[30:31], 0, v[142:143]
	s_add_i32 m0, s75, 0xe000
	s_nop 0
	global_load_lds_dwordx4 v[214:215], off sc1
	s_setprio 1
	s_waitcnt vmcnt(8) lgkmcnt(0)
	s_barrier
	v_mfma_f32_16x16x32_bf16 v[124:127], v[146:149], v[182:185], v[124:127]
	v_mfma_f32_16x16x32_bf16 v[120:123], v[158:161], v[182:185], v[120:123]
	v_mfma_f32_16x16x32_bf16 v[108:111], v[146:149], v[190:193], v[108:111]
	v_mfma_f32_16x16x32_bf16 v[104:107], v[158:161], v[190:193], v[104:107]
	v_mfma_f32_16x16x32_bf16 v[92:95], v[146:149], v[198:201], v[92:95]
	v_mfma_f32_16x16x32_bf16 v[88:91], v[158:161], v[198:201], v[88:91]
	v_mfma_f32_16x16x32_bf16 v[76:79], v[146:149], v[206:209], v[76:79]
	v_mfma_f32_16x16x32_bf16 v[72:75], v[158:161], v[206:209], v[72:75]
	v_mfma_f32_16x16x32_bf16 v[124:127], v[154:157], v[186:189], v[124:127]
	v_mfma_f32_16x16x32_bf16 v[120:123], v[162:165], v[186:189], v[120:123]
	v_mfma_f32_16x16x32_bf16 v[108:111], v[154:157], v[194:197], v[108:111]
	v_mfma_f32_16x16x32_bf16 v[104:107], v[162:165], v[194:197], v[104:107]
	v_mfma_f32_16x16x32_bf16 v[92:95], v[154:157], v[202:205], v[92:95]
	v_mfma_f32_16x16x32_bf16 v[88:91], v[162:165], v[202:205], v[88:91]
	v_mfma_f32_16x16x32_bf16 v[76:79], v[154:157], v[210:213], v[76:79]
	v_mfma_f32_16x16x32_bf16 v[72:75], v[162:165], v[210:213], v[72:75]
	v_mfma_f32_16x16x32_bf16 v[116:119], v[166:169], v[182:185], v[116:119]
	v_mfma_f32_16x16x32_bf16 v[112:115], v[174:177], v[182:185], v[112:115]
	v_mfma_f32_16x16x32_bf16 v[100:103], v[166:169], v[190:193], v[100:103]
	v_mfma_f32_16x16x32_bf16 v[96:99], v[174:177], v[190:193], v[96:99]
	v_mfma_f32_16x16x32_bf16 v[84:87], v[166:169], v[198:201], v[84:87]
	v_mfma_f32_16x16x32_bf16 v[80:83], v[174:177], v[198:201], v[80:83]
	v_mfma_f32_16x16x32_bf16 v[68:71], v[166:169], v[206:209], v[68:71]
	v_mfma_f32_16x16x32_bf16 v[64:67], v[174:177], v[206:209], v[64:67]
	v_mfma_f32_16x16x32_bf16 v[116:119], v[170:173], v[186:189], v[116:119]
	v_mfma_f32_16x16x32_bf16 v[112:115], v[178:181], v[186:189], v[112:115]
	v_mfma_f32_16x16x32_bf16 v[100:103], v[170:173], v[194:197], v[100:103]
	v_mfma_f32_16x16x32_bf16 v[96:99], v[178:181], v[194:197], v[96:99]
	v_mfma_f32_16x16x32_bf16 v[84:87], v[170:173], v[202:205], v[84:87]
	v_mfma_f32_16x16x32_bf16 v[80:83], v[178:181], v[202:205], v[80:83]
	v_mfma_f32_16x16x32_bf16 v[68:71], v[170:173], v[210:213], v[68:71]
	v_mfma_f32_16x16x32_bf16 v[64:67], v[178:181], v[210:213], v[64:67]
	s_barrier
	s_setprio 0
	s_add_i32 s54, s86, s48
	v_lshl_add_u64 v[214:215], s[34:35], 0, v[132:133]
	s_mov_b32 m0, s54
	ds_read_b128 v[182:185], v153 offset:16384
	ds_read_b128 v[186:189], v153 offset:17408
	ds_read_b128 v[190:193], v153 offset:18432
	ds_read_b128 v[194:197], v153 offset:19456
	ds_read_b128 v[198:201], v153 offset:20480
	ds_read_b128 v[202:205], v153 offset:21504
	ds_read_b128 v[206:209], v153 offset:22528
	ds_read_b128 v[210:213], v153 offset:23552
	global_load_lds_dwordx4 v[214:215], off sc1
	s_add_i32 m0, s54, 0x2000
	s_add_u32 s64, s34, 0x80000
	v_lshl_add_u64 v[216:217], s[34:35], 0, v[128:129]
	s_addc_u32 s65, s35, 0
	s_add_i32 s54, s87, s48
	global_load_lds_dwordx4 v[216:217], off sc1
	v_lshl_add_u64 v[218:219], s[64:65], 0, v[132:133]
	s_mov_b32 m0, s54
	v_lshl_add_u64 v[220:221], s[36:37], 0, v[130:131]
	global_load_lds_dwordx4 v[218:219], off sc1
	v_lshl_add_u64 v[218:219], s[64:65], 0, v[128:129]
	s_add_i32 m0, s54, 0x2000
	s_nop 0
	global_load_lds_dwordx4 v[218:219], off sc1
	v_lshl_add_u64 v[218:219], s[36:37], 0, v[134:135]
	s_mov_b32 m0, s75
	s_nop 0
	global_load_lds_dwordx4 v[218:219], off sc1
	s_mov_b32 m0, s76
	s_nop 0
	global_load_lds_dwordx4 v[220:221], off sc1
	s_setprio 1
	s_waitcnt vmcnt(8) lgkmcnt(0)
	s_barrier
; #define PG8_STAGE(bufoff, gbase, voff) do { _Pragma("unroll") for (int _i = 0; _i < 2; ++_i) \
;         __builtin_amdgcn_global_load_lds((const unsigned*)((const char*)(gbase) + (voff)[_i]), (LAS unsigned*)(lds + (bufoff) + ldsw + _i * 8192), 16, 0, 0); } while (0)
; #define PG8_LDA(dst, b, h) do { _Pragma("unroll") for (int m = 0; m < 4; ++m) _Pragma("unroll") for (int k = 0; k < 2; ++k) dst[m][k] = *(const LAS bf16x8*)(lds + PG8_SA(b, h) + aoff + m * 2048 + k * KOFF); } while (0)
; #define PG8_LDB(dst, b, h) do { _Pragma("unroll") for (int n = 0; n < 2; ++n) _Pragma("unroll") for (int k = 0; k < 2; ++k) dst[n][k] = *(const LAS bf16x8*)(lds + PG8_SB(b, h) + boff + n * 2048 + k * KOFF); } while (0)
; #define PG8_WAIT_V(n) asm volatile("s_waitcnt vmcnt(" #n ")" ::: "memory")
; #define PG8_WAIT_L(n) asm volatile("s_waitcnt lgkmcnt(" #n ")" ::: "memory")
; #define PG8_BAR __builtin_amdgcn_s_barrier()
; #define PG8_SCHED __builtin_amdgcn_sched_barrier(0)
; template <class Epi, bool ALIGN_EPI = true, bool FP8 = false>
; __device__ __forceinline__ void gemm_phase(LAS unsigned char* lds, const Gemm g, const StaticOrder& S, const Epi& E, const int wid) {
;     ...
;             PG8_LDB(B0, 1, 0); PG8_LDB(B1, 1, 1); PG8_SCHED; PG8_LDA(At, 1, 0); PG8_STAGE(PG8_SA(0, 1), a2 + hstep, voffA);
;             PG8_WAIT_V(8); PG8_WAIT_L(0); PG8_BAR; PG8_MMA(0, 0, At, B0); PG8_MMA(0, 1, At, B1); PG8_BAR; PG8_SCHED;
;             PG8_LDA(At, 1, 1); PG8_STAGE(PG8_SB(1, 0), b3, voffB); PG8_STAGE(PG8_SB(1, 1), b3 + hstep, voffB); PG8_STAGE(PG8_SA(1, 0), a3, voffA);
;             PG8_WAIT_V(8); PG8_WAIT_L(0); PG8_BAR; PG8_MMA(1, 0, At, B0); PG8_MMA(1, 1, At, B1); PG8_BAR; PG8_SCHED;
	v_mfma_f32_16x16x32_bf16 v[60:63], v[146:149], v[182:185], v[60:63]
	v_mfma_f32_16x16x32_bf16 v[56:59], v[158:161], v[182:185], v[56:59]
	v_mfma_f32_16x16x32_bf16 v[44:47], v[146:149], v[190:193], v[44:47]
	v_mfma_f32_16x16x32_bf16 v[40:43], v[158:161], v[190:193], v[40:43]
	v_mfma_f32_16x16x32_bf16 v[28:31], v[146:149], v[198:201], v[28:31]
	v_mfma_f32_16x16x32_bf16 v[24:27], v[158:161], v[198:201], v[24:27]
	v_mfma_f32_16x16x32_bf16 v[12:15], v[146:149], v[206:209], v[12:15]
	v_mfma_f32_16x16x32_bf16 v[8:11], v[158:161], v[206:209], v[8:11]
	v_mfma_f32_16x16x32_bf16 v[60:63], v[154:157], v[186:189], v[60:63]
	v_mfma_f32_16x16x32_bf16 v[56:59], v[162:165], v[186:189], v[56:59]
	v_mfma_f32_16x16x32_bf16 v[44:47], v[154:157], v[194:197], v[44:47]
	v_mfma_f32_16x16x32_bf16 v[40:43], v[162:165], v[194:197], v[40:43]
	v_mfma_f32_16x16x32_bf16 v[28:31], v[154:157], v[202:205], v[28:31]
	v_mfma_f32_16x16x32_bf16 v[24:27], v[162:165], v[202:205], v[24:27]
	v_mfma_f32_16x16x32_bf16 v[12:15], v[154:157], v[210:213], v[12:15]
	v_mfma_f32_16x16x32_bf16 v[8:11], v[162:165], v[210:213], v[8:11]
	v_mfma_f32_16x16x32_bf16 v[52:55], v[166:169], v[182:185], v[52:55]
	v_mfma_f32_16x16x32_bf16 v[48:51], v[174:177], v[182:185], v[48:51]
	v_mfma_f32_16x16x32_bf16 v[36:39], v[166:169], v[190:193], v[36:39]
	v_mfma_f32_16x16x32_bf16 v[32:35], v[174:177], v[190:193], v[32:35]
	v_mfma_f32_16x16x32_bf16 v[20:23], v[166:169], v[198:201], v[20:23]
	v_mfma_f32_16x16x32_bf16 v[16:19], v[174:177], v[198:201], v[16:19]
	v_mfma_f32_16x16x32_bf16 v[4:7], v[166:169], v[206:209], v[4:7]
	v_mfma_f32_16x16x32_bf16 v[0:3], v[174:177], v[206:209], v[0:3]
	v_mfma_f32_16x16x32_bf16 v[52:55], v[170:173], v[186:189], v[52:55]
	v_mfma_f32_16x16x32_bf16 v[48:51], v[178:181], v[186:189], v[48:51]
	v_mfma_f32_16x16x32_bf16 v[36:39], v[170:173], v[194:197], v[36:39]
	v_mfma_f32_16x16x32_bf16 v[32:35], v[178:181], v[194:197], v[32:35]
	v_mfma_f32_16x16x32_bf16 v[20:23], v[170:173], v[202:205], v[20:23]
	v_mfma_f32_16x16x32_bf16 v[16:19], v[178:181], v[202:205], v[16:19]
	v_mfma_f32_16x16x32_bf16 v[4:7], v[170:173], v[210:213], v[4:7]
	v_mfma_f32_16x16x32_bf16 v[0:3], v[178:181], v[210:213], v[0:3]
	s_barrier
	s_setprio 0
	s_add_i32 s54, 0, 0x18000
	s_add_i32 s64, 0, 0x1c000
	v_add_u32_e32 v162, s54, v150
	v_add_u32_e32 v178, s64, v150
	ds_read_b128 v[146:149], v162
	ds_read_b128 v[154:157], v162 offset:1024
	ds_read_b128 v[158:161], v162 offset:2048
	ds_read_b128 v[162:165], v162 offset:3072
	ds_read_b128 v[166:169], v178
	ds_read_b128 v[170:173], v178 offset:1024
	ds_read_b128 v[174:177], v178 offset:2048
	ds_read_b128 v[178:181], v178 offset:3072
	s_add_u32 s36, s36, 0x80000
	s_addc_u32 s37, s37, 0
	s_mov_b32 m0, s77
	v_lshl_add_u64 v[222:223], s[36:37], 0, v[134:135]
	ds_read_b128 v[182:185], v153 offset:32768
	ds_read_b128 v[186:189], v153 offset:33792
	ds_read_b128 v[190:193], v153 offset:34816
	ds_read_b128 v[194:197], v153 offset:35840
	ds_read_b128 v[198:201], v153 offset:36864
	ds_read_b128 v[202:205], v153 offset:37888
	ds_read_b128 v[206:209], v153 offset:38912
	ds_read_b128 v[210:213], v153 offset:39936
	global_load_lds_dwordx4 v[222:223], off sc1
	v_lshl_add_u64 v[222:223], s[36:37], 0, v[130:131]
	s_mov_b32 m0, s78
	s_nop 0
	global_load_lds_dwordx4 v[222:223], off sc1
	s_setprio 1
	s_waitcnt vmcnt(8) lgkmcnt(0)
	s_barrier
	v_mfma_f32_16x16x32_bf16 v[124:127], v[146:149], v[182:185], v[124:127]
	v_mfma_f32_16x16x32_bf16 v[120:123], v[158:161], v[182:185], v[120:123]
	v_mfma_f32_16x16x32_bf16 v[108:111], v[146:149], v[190:193], v[108:111]
	v_mfma_f32_16x16x32_bf16 v[104:107], v[158:161], v[190:193], v[104:107]
	v_mfma_f32_16x16x32_bf16 v[92:95], v[146:149], v[198:201], v[92:95]
	v_mfma_f32_16x16x32_bf16 v[88:91], v[158:161], v[198:201], v[88:91]
	v_mfma_f32_16x16x32_bf16 v[76:79], v[146:149], v[206:209], v[76:79]
	v_mfma_f32_16x16x32_bf16 v[72:75], v[158:161], v[206:209], v[72:75]
	v_mfma_f32_16x16x32_bf16 v[124:127], v[154:157], v[186:189], v[124:127]
	v_mfma_f32_16x16x32_bf16 v[120:123], v[162:165], v[186:189], v[120:123]
	v_mfma_f32_16x16x32_bf16 v[108:111], v[154:157], v[194:197], v[108:111]
	v_mfma_f32_16x16x32_bf16 v[104:107], v[162:165], v[194:197], v[104:107]
	v_mfma_f32_16x16x32_bf16 v[92:95], v[154:157], v[202:205], v[92:95]
	v_mfma_f32_16x16x32_bf16 v[88:91], v[162:165], v[202:205], v[88:91]
	v_mfma_f32_16x16x32_bf16 v[76:79], v[154:157], v[210:213], v[76:79]
	v_mfma_f32_16x16x32_bf16 v[72:75], v[162:165], v[210:213], v[72:75]
	v_mfma_f32_16x16x32_bf16 v[116:119], v[166:169], v[182:185], v[116:119]
	v_mfma_f32_16x16x32_bf16 v[112:115], v[174:177], v[182:185], v[112:115]
	v_mfma_f32_16x16x32_bf16 v[100:103], v[166:169], v[190:193], v[100:103]
	v_mfma_f32_16x16x32_bf16 v[96:99], v[174:177], v[190:193], v[96:99]
	v_mfma_f32_16x16x32_bf16 v[84:87], v[166:169], v[198:201], v[84:87]
	v_mfma_f32_16x16x32_bf16 v[80:83], v[174:177], v[198:201], v[80:83]
	v_mfma_f32_16x16x32_bf16 v[68:71], v[166:169], v[206:209], v[68:71]
	v_mfma_f32_16x16x32_bf16 v[64:67], v[174:177], v[206:209], v[64:67]
	v_mfma_f32_16x16x32_bf16 v[116:119], v[170:173], v[186:189], v[116:119]
	v_mfma_f32_16x16x32_bf16 v[112:115], v[178:181], v[186:189], v[112:115]
	v_mfma_f32_16x16x32_bf16 v[100:103], v[170:173], v[194:197], v[100:103]
	v_mfma_f32_16x16x32_bf16 v[96:99], v[178:181], v[194:197], v[96:99]
	v_mfma_f32_16x16x32_bf16 v[84:87], v[170:173], v[202:205], v[84:87]
	v_mfma_f32_16x16x32_bf16 v[80:83], v[178:181], v[202:205], v[80:83]
	v_mfma_f32_16x16x32_bf16 v[68:71], v[170:173], v[210:213], v[68:71]
	v_mfma_f32_16x16x32_bf16 v[64:67], v[178:181], v[210:213], v[64:67]
	s_barrier
; #define PG8_STAGE(bufoff, gbase, voff) do { _Pragma("unroll") for (int _i = 0; _i < 2; ++_i) \
;         __builtin_amdgcn_global_load_lds((const unsigned*)((const char*)(gbase) + (voff)[_i]), (LAS unsigned*)(lds + (bufoff) + ldsw + _i * 8192), 16, 0, 0); } while (0)
; #define PG8_LDA(dst, b, h) do { _Pragma("unroll") for (int m = 0; m < 4; ++m) _Pragma("unroll") for (int k = 0; k < 2; ++k) dst[m][k] = *(const LAS bf16x8*)(lds + PG8_SA(b, h) + aoff + m * 2048 + k * KOFF); } while (0)
; #define PG8_WAIT_V(n) asm volatile("s_waitcnt vmcnt(" #n ")" ::: "memory")
; #define PG8_WAIT_L(n) asm volatile("s_waitcnt lgkmcnt(" #n ")" ::: "memory")
; #define PG8_BAR __builtin_amdgcn_s_barrier()
; #define PG8_SCHED __builtin_amdgcn_sched_barrier(0)
; template <class Epi, bool ALIGN_EPI = true, bool FP8 = false>
; __device__ __forceinline__ void gemm_phase(LAS unsigned char* lds, const Gemm g, const StaticOrder& S, const Epi& E, const int wid) {
;     ...
;             PG8_LDA(At, 1, 1); PG8_STAGE(PG8_SB(1, 0), b3, voffB); PG8_STAGE(PG8_SB(1, 1), b3 + hstep, voffB); PG8_STAGE(PG8_SA(1, 0), a3, voffA);
;             PG8_WAIT_V(8); PG8_WAIT_L(0); PG8_BAR; PG8_MMA(1, 0, At, B0); PG8_MMA(1, 1, At, B1); PG8_BAR; PG8_SCHED;
;         }
	s_setprio 0
	s_add_i32 s36, s54, s48
	v_lshl_add_u64 v[214:215], v[214:215], 0, s[16:17]
	s_mov_b32 m0, s36
	ds_read_b128 v[182:185], v153 offset:49152
	ds_read_b128 v[186:189], v153 offset:50176
	ds_read_b128 v[190:193], v153 offset:51200
	ds_read_b128 v[194:197], v153 offset:52224
	ds_read_b128 v[198:201], v153 offset:53248
	ds_read_b128 v[202:205], v153 offset:54272
	ds_read_b128 v[206:209], v153 offset:55296
	ds_read_b128 v[210:213], v153 offset:56320
	global_load_lds_dwordx4 v[214:215], off sc1
	s_add_i32 m0, s36, 0x2000
	s_add_u32 s34, s34, 0x80080
	v_lshl_add_u64 v[214:215], v[216:217], 0, s[16:17]
	s_addc_u32 s35, s35, 0
	s_add_i32 s36, s64, s48
	global_load_lds_dwordx4 v[214:215], off sc1
	v_lshl_add_u64 v[214:215], s[34:35], 0, v[132:133]
	s_mov_b32 m0, s36
	s_nop 0
	global_load_lds_dwordx4 v[214:215], off sc1
	v_lshl_add_u64 v[214:215], s[34:35], 0, v[128:129]
	s_add_i32 m0, s36, 0x2000
	s_nop 0
	global_load_lds_dwordx4 v[214:215], off sc1
	v_lshl_add_u64 v[214:215], v[218:219], 0, s[16:17]
	s_mov_b32 m0, s83
	s_nop 0
	global_load_lds_dwordx4 v[214:215], off sc1
	v_lshl_add_u64 v[214:215], v[220:221], 0, s[16:17]
	s_mov_b32 m0, s84
	s_nop 0
	global_load_lds_dwordx4 v[214:215], off sc1
	s_setprio 1
	s_waitcnt vmcnt(8) lgkmcnt(0)
	s_barrier
	v_mfma_f32_16x16x32_bf16 v[60:63], v[146:149], v[182:185], v[60:63]
	v_mfma_f32_16x16x32_bf16 v[56:59], v[158:161], v[182:185], v[56:59]
	v_mfma_f32_16x16x32_bf16 v[44:47], v[146:149], v[190:193], v[44:47]
	v_mfma_f32_16x16x32_bf16 v[40:43], v[158:161], v[190:193], v[40:43]
	v_mfma_f32_16x16x32_bf16 v[28:31], v[146:149], v[198:201], v[28:31]
	v_mfma_f32_16x16x32_bf16 v[24:27], v[158:161], v[198:201], v[24:27]
	v_mfma_f32_16x16x32_bf16 v[12:15], v[146:149], v[206:209], v[12:15]
	v_mfma_f32_16x16x32_bf16 v[8:11], v[158:161], v[206:209], v[8:11]
	v_mfma_f32_16x16x32_bf16 v[60:63], v[154:157], v[186:189], v[60:63]
	v_mfma_f32_16x16x32_bf16 v[56:59], v[162:165], v[186:189], v[56:59]
	v_mfma_f32_16x16x32_bf16 v[44:47], v[154:157], v[194:197], v[44:47]
	v_mfma_f32_16x16x32_bf16 v[40:43], v[162:165], v[194:197], v[40:43]
	v_mfma_f32_16x16x32_bf16 v[28:31], v[154:157], v[202:205], v[28:31]
	v_mfma_f32_16x16x32_bf16 v[24:27], v[162:165], v[202:205], v[24:27]
	v_mfma_f32_16x16x32_bf16 v[12:15], v[154:157], v[210:213], v[12:15]
	v_mfma_f32_16x16x32_bf16 v[8:11], v[162:165], v[210:213], v[8:11]
	v_mfma_f32_16x16x32_bf16 v[52:55], v[166:169], v[182:185], v[52:55]
	v_mfma_f32_16x16x32_bf16 v[48:51], v[174:177], v[182:185], v[48:51]
	v_mfma_f32_16x16x32_bf16 v[36:39], v[166:169], v[190:193], v[36:39]
	v_mfma_f32_16x16x32_bf16 v[32:35], v[174:177], v[190:193], v[32:35]
	v_mfma_f32_16x16x32_bf16 v[20:23], v[166:169], v[198:201], v[20:23]
	v_mfma_f32_16x16x32_bf16 v[16:19], v[174:177], v[198:201], v[16:19]
	v_mfma_f32_16x16x32_bf16 v[4:7], v[166:169], v[206:209], v[4:7]
	v_mfma_f32_16x16x32_bf16 v[0:3], v[174:177], v[206:209], v[0:3]
	v_mfma_f32_16x16x32_bf16 v[52:55], v[170:173], v[186:189], v[52:55]
	v_mfma_f32_16x16x32_bf16 v[48:51], v[178:181], v[186:189], v[48:51]
	v_mfma_f32_16x16x32_bf16 v[36:39], v[170:173], v[194:197], v[36:39]
	v_mfma_f32_16x16x32_bf16 v[32:35], v[178:181], v[194:197], v[32:35]
	v_mfma_f32_16x16x32_bf16 v[20:23], v[170:173], v[202:205], v[20:23]
	v_mfma_f32_16x16x32_bf16 v[16:19], v[178:181], v[202:205], v[16:19]
	v_mfma_f32_16x16x32_bf16 v[4:7], v[170:173], v[210:213], v[4:7]
	v_mfma_f32_16x16x32_bf16 v[0:3], v[178:181], v[210:213], v[0:3]
	s_barrier
	s_setprio 0
	s_add_u32 s30, s30, 0x100
	s_addc_u32 s31, s31, 0
	s_add_u32 s42, s42, 0x100
	s_addc_u32 s43, s43, 0
	s_cmp_ge_u32 s52, s9
	s_mov_b32 s34, s52
	s_cbranch_scc0 .LBB0_506
	s_and_b64 vcc, exec, s[12:13]
	s_cbranch_vccz .LBB0_509

; #define PG8_STAGE(bufoff, gbase, voff) do { _Pragma("unroll") for (int _i = 0; _i < 2; ++_i) \
;         __builtin_amdgcn_global_load_lds((const unsigned*)((const char*)(gbase) + (voff)[_i]), (LAS unsigned*)(lds + (bufoff) + ldsw + _i * 8192), 16, 0, 0); } while (0)
; #define PG8_LDA(dst, b, h) do { _Pragma("unroll") for (int m = 0; m < 4; ++m) _Pragma("unroll") for (int k = 0; k < 2; ++k) dst[m][k] = *(const LAS bf16x8*)(lds + PG8_SA(b, h) + aoff + m * 2048 + k * KOFF); } while (0)
; #define PG8_LDB(dst, b, h) do { _Pragma("unroll") for (int n = 0; n < 2; ++n) _Pragma("unroll") for (int k = 0; k < 2; ++k) dst[n][k] = *(const LAS bf16x8*)(lds + PG8_SB(b, h) + boff + n * 2048 + k * KOFF); } while (0)
; #define PG8_WAIT_V(n) asm volatile("s_waitcnt vmcnt(" #n ")" ::: "memory")
; #define PG8_WAIT_L(n) asm volatile("s_waitcnt lgkmcnt(" #n ")" ::: "memory")
; #define PG8_BAR __builtin_amdgcn_s_barrier()
; #define PG8_SCHED __builtin_amdgcn_sched_barrier(0)
; template <class Epi, bool ALIGN_EPI = true, bool FP8 = false>
; __device__ __forceinline__ void gemm_phase(LAS unsigned char* lds, const Gemm g, const StaticOrder& S, const Epi& E, const int wid) {
;     ...
;             const char* a1 = cA + (size_t)(t + 1) * kstep;
;             const char* a2 = last ? nA : cA + (size_t)(t + 2) * kstep; const char* b2 = last ? nB : cB + (size_t)(t + 2) * kstep;
;             const char* a3 = a2 + kstep; const char* b3 = b2 + kstep;
;             PG8_LDB(B0, 0, 0); PG8_LDB(B1, 0, 1); PG8_SCHED; PG8_LDA(At, 0, 0); PG8_STAGE(PG8_SA(1, 1), a1 + hstep, voffA);
;             PG8_WAIT_V(8); PG8_WAIT_L(0); PG8_BAR; PG8_MMA(0, 0, At, B0); PG8_MMA(0, 1, At, B1); PG8_BAR; PG8_SCHED;
;             PG8_LDA(At, 0, 1); PG8_STAGE(PG8_SB(0, 0), b2, voffB); PG8_STAGE(PG8_SB(0, 1), b2 + hstep, voffB); PG8_STAGE(PG8_SA(0, 0), a2, voffA);
;             PG8_WAIT_V(8); PG8_WAIT_L(0); PG8_BAR; PG8_MMA(1, 0, At, B0); PG8_MMA(1, 1, At, B1); PG8_BAR; PG8_SCHED;
;             PG8_LDB(B0, 1, 0); PG8_LDB(B1, 1, 1); PG8_SCHED; PG8_LDA(At, 1, 0); PG8_STAGE(PG8_SA(0, 1), a2 + hstep, voffA);
;             PG8_WAIT_V(8); PG8_WAIT_L(0); PG8_BAR; PG8_MMA(0, 0, At, B0); PG8_MMA(0, 1, At, B1); PG8_BAR; PG8_SCHED;
;             PG8_LDA(At, 1, 1); PG8_STAGE(PG8_SB(1, 0), b3, voffB); PG8_STAGE(PG8_SB(1, 1), b3 + hstep, voffB); PG8_STAGE(PG8_SA(1, 0), a3, voffA);
.LBB0_572:
	ds_read_b128 v[152:155], v190
	ds_read_b128 v[156:159], v190 offset:1024
	ds_read_b128 v[144:147], v190 offset:2048
	ds_read_b128 v[148:151], v190 offset:3072
	ds_read_b128 v[136:139], v191
	ds_read_b128 v[140:143], v191 offset:1024
	ds_read_b128 v[128:131], v191 offset:2048
	ds_read_b128 v[132:135], v191 offset:3072
	s_add_i32 s3, s34, 2
	s_add_u32 s35, s30, 0xfffc0080
	s_addc_u32 s36, s31, -1
	s_cmp_eq_u32 s86, s34
	s_cselect_b32 s34, s85, s87
	s_cselect_b32 s37, s21, s36
	s_cselect_b32 s36, s23, s35
	s_cselect_b32 s35, s84, s88
	v_lshl_add_u64 v[220:221], s[30:31], 0, v[170:171]
	s_add_i32 m0, s27, 0xc000
	ds_read_b128 v[178:181], v192
	ds_read_b128 v[182:185], v192 offset:1024
	ds_read_b128 v[196:199], v192 offset:2048
	ds_read_b128 v[200:203], v192 offset:3072
	ds_read_b128 v[204:207], v192 offset:4096
	ds_read_b128 v[208:211], v192 offset:5120
	ds_read_b128 v[212:215], v192 offset:6144
	ds_read_b128 v[216:219], v192 offset:7168
	global_load_lds_dwordx4 v[220:221], off sc1
	v_lshl_add_u64 v[220:221], s[30:31], 0, v[172:173]
	s_add_i32 m0, s27, 0xe000
	s_nop 0
	global_load_lds_dwordx4 v[220:221], off sc1
	s_setprio 1
	s_waitcnt vmcnt(8) lgkmcnt(0)
	s_barrier
	v_mfma_f32_16x16x128_f8f6f4 v[120:123], v[152:159], v[178:185], v[120:123]
	v_mfma_f32_16x16x128_f8f6f4 v[124:127], v[144:151], v[178:185], v[124:127]
	v_mfma_f32_16x16x128_f8f6f4 v[112:115], v[152:159], v[196:203], v[112:115]
	v_mfma_f32_16x16x128_f8f6f4 v[116:119], v[144:151], v[196:203], v[116:119]
	v_mfma_f32_16x16x128_f8f6f4 v[104:107], v[152:159], v[204:211], v[104:107]
	v_mfma_f32_16x16x128_f8f6f4 v[108:111], v[144:151], v[204:211], v[108:111]
	v_mfma_f32_16x16x128_f8f6f4 v[88:91], v[152:159], v[212:219], v[88:91]
	v_mfma_f32_16x16x128_f8f6f4 v[92:95], v[144:151], v[212:219], v[92:95]
	v_mfma_f32_16x16x128_f8f6f4 v[96:99], v[136:143], v[178:185], v[96:99]
	v_mfma_f32_16x16x128_f8f6f4 v[100:103], v[128:135], v[178:185], v[100:103]
	v_mfma_f32_16x16x128_f8f6f4 v[80:83], v[136:143], v[196:203], v[80:83]
	v_mfma_f32_16x16x128_f8f6f4 v[84:87], v[128:135], v[196:203], v[84:87]
	v_mfma_f32_16x16x128_f8f6f4 v[72:75], v[136:143], v[204:211], v[72:75]
	v_mfma_f32_16x16x128_f8f6f4 v[76:79], v[128:135], v[204:211], v[76:79]
	v_mfma_f32_16x16x128_f8f6f4 v[64:67], v[136:143], v[212:219], v[64:67]
	v_mfma_f32_16x16x128_f8f6f4 v[68:71], v[128:135], v[212:219], v[68:71]
	s_barrier
	s_setprio 0
	s_add_i32 s42, s75, s48
	v_lshl_add_u64 v[178:179], s[34:35], 0, v[164:165]
	s_mov_b32 m0, s42
	ds_read_b128 v[196:199], v192 offset:16384
	ds_read_b128 v[200:203], v192 offset:17408
	ds_read_b128 v[204:207], v192 offset:18432
	ds_read_b128 v[208:211], v192 offset:19456
	ds_read_b128 v[212:215], v192 offset:20480
	ds_read_b128 v[216:219], v192 offset:21504
	ds_read_b128 v[220:223], v192 offset:22528
	ds_read_b128 v[224:227], v192 offset:23552
	global_load_lds_dwordx4 v[178:179], off sc1
	s_add_i32 m0, s42, 0x2000
	s_add_u32 s42, s34, 0x40000
	v_lshl_add_u64 v[180:181], s[34:35], 0, v[160:161]
	s_addc_u32 s43, s35, 0
	s_add_i32 s52, s76, s48
	global_load_lds_dwordx4 v[180:181], off sc1
	v_lshl_add_u64 v[182:183], s[42:43], 0, v[164:165]
	s_mov_b32 m0, s52
	v_lshl_add_u64 v[184:185], s[36:37], 0, v[162:163]
	global_load_lds_dwordx4 v[182:183], off sc1
	v_lshl_add_u64 v[182:183], s[42:43], 0, v[160:161]
	s_add_i32 m0, s52, 0x2000
	s_nop 0
	global_load_lds_dwordx4 v[182:183], off sc1
	v_lshl_add_u64 v[182:183], s[36:37], 0, v[166:167]
	s_mov_b32 m0, s27
	s_nop 0
	global_load_lds_dwordx4 v[182:183], off sc1
	s_mov_b32 m0, s55
	s_nop 0
	global_load_lds_dwordx4 v[184:185], off sc1
	s_setprio 1
	s_waitcnt vmcnt(8) lgkmcnt(0)
	s_barrier
	v_mfma_f32_16x16x128_f8f6f4 v[56:59], v[152:159], v[196:203], v[56:59]
	v_mfma_f32_16x16x128_f8f6f4 v[60:63], v[144:151], v[196:203], v[60:63]
	v_mfma_f32_16x16x128_f8f6f4 v[48:51], v[152:159], v[204:211], v[48:51]
	v_mfma_f32_16x16x128_f8f6f4 v[52:55], v[144:151], v[204:211], v[52:55]
	v_mfma_f32_16x16x128_f8f6f4 v[40:43], v[152:159], v[212:219], v[40:43]
	v_mfma_f32_16x16x128_f8f6f4 v[44:47], v[144:151], v[212:219], v[44:47]
	v_mfma_f32_16x16x128_f8f6f4 v[228:231], v[152:159], v[220:227], v[24:27]
	v_mfma_f32_16x16x128_f8f6f4 v[232:235], v[144:151], v[220:227], v[28:31]
	v_mfma_f32_16x16x128_f8f6f4 v[236:239], v[136:143], v[196:203], v[32:35]
	v_mfma_f32_16x16x128_f8f6f4 v[240:243], v[128:135], v[196:203], v[36:39]
	v_mfma_f32_16x16x128_f8f6f4 v[244:247], v[136:143], v[204:211], v[16:19]
	v_mfma_f32_16x16x128_f8f6f4 v[204:207], v[128:135], v[204:211], v[20:23]
	v_mfma_f32_16x16x128_f8f6f4 v[208:211], v[136:143], v[212:219], v[8:11]
	v_mfma_f32_16x16x128_f8f6f4 v[212:215], v[128:135], v[212:219], v[12:15]
	v_mfma_f32_16x16x128_f8f6f4 v[216:219], v[136:143], v[220:227], v[0:3]
	v_mfma_f32_16x16x128_f8f6f4 v[220:223], v[128:135], v[220:227], v[4:7]
	s_barrier
	s_setprio 0
	s_add_i32 s42, 0, 0x18000
	s_add_i32 s43, 0, 0x1c000
	s_nop 0
	v_add_u32_e32 v12, s42, v187
	v_add_u32_e32 v16, s43, v187
	ds_read_b128 v[0:3], v12
	ds_read_b128 v[4:7], v12 offset:1024
	ds_read_b128 v[8:11], v12 offset:2048
	ds_read_b128 v[12:15], v12 offset:3072
	ds_read_b128 v[128:131], v16
	ds_read_b128 v[132:135], v16 offset:1024
	ds_read_b128 v[136:139], v16 offset:2048
	ds_read_b128 v[140:143], v16 offset:3072
	s_add_u32 s36, s36, 0x40000
	s_addc_u32 s37, s37, 0
	s_mov_b32 m0, s64
	v_lshl_add_u64 v[152:153], s[36:37], 0, v[166:167]
	ds_read_b128 v[16:19], v192 offset:32768
	ds_read_b128 v[20:23], v192 offset:33792
	ds_read_b128 v[24:27], v192 offset:34816
	ds_read_b128 v[28:31], v192 offset:35840
	ds_read_b128 v[32:35], v192 offset:36864
	ds_read_b128 v[36:39], v192 offset:37888
	ds_read_b128 v[144:147], v192 offset:38912
	ds_read_b128 v[148:151], v192 offset:39936
	global_load_lds_dwordx4 v[152:153], off sc1
	v_lshl_add_u64 v[152:153], s[36:37], 0, v[162:163]
	s_mov_b32 m0, s65
	s_nop 0
	global_load_lds_dwordx4 v[152:153], off sc1
	s_setprio 1
	s_waitcnt vmcnt(8) lgkmcnt(0)
	s_barrier
; #define PG8_STAGE(bufoff, gbase, voff) do { _Pragma("unroll") for (int _i = 0; _i < 2; ++_i) \
;         __builtin_amdgcn_global_load_lds((const unsigned*)((const char*)(gbase) + (voff)[_i]), (LAS unsigned*)(lds + (bufoff) + ldsw + _i * 8192), 16, 0, 0); } while (0)
; #define PG8_LDA(dst, b, h) do { _Pragma("unroll") for (int m = 0; m < 4; ++m) _Pragma("unroll") for (int k = 0; k < 2; ++k) dst[m][k] = *(const LAS bf16x8*)(lds + PG8_SA(b, h) + aoff + m * 2048 + k * KOFF); } while (0)
; #define PG8_WAIT_V(n) asm volatile("s_waitcnt vmcnt(" #n ")" ::: "memory")
; #define PG8_WAIT_L(n) asm volatile("s_waitcnt lgkmcnt(" #n ")" ::: "memory")
; #define PG8_BAR __builtin_amdgcn_s_barrier()
; #define PG8_SCHED __builtin_amdgcn_sched_barrier(0)
; template <class Epi, bool ALIGN_EPI = true, bool FP8 = false>
; __device__ __forceinline__ void gemm_phase(LAS unsigned char* lds, const Gemm g, const StaticOrder& S, const Epi& E, const int wid) {
;     ...
;             PG8_LDA(At, 1, 1); PG8_STAGE(PG8_SB(1, 0), b3, voffB); PG8_STAGE(PG8_SB(1, 1), b3 + hstep, voffB); PG8_STAGE(PG8_SA(1, 0), a3, voffA);
;             PG8_WAIT_V(8); PG8_WAIT_L(0); PG8_BAR; PG8_MMA(1, 0, At, B0); PG8_MMA(1, 1, At, B1); PG8_BAR; PG8_SCHED;
;         }
	v_mfma_f32_16x16x128_f8f6f4 v[120:123], v[0:7], v[16:23], v[120:123]
	v_mfma_f32_16x16x128_f8f6f4 v[124:127], v[8:15], v[16:23], v[124:127]
	v_mfma_f32_16x16x128_f8f6f4 v[112:115], v[0:7], v[24:31], v[112:115]
	v_mfma_f32_16x16x128_f8f6f4 v[116:119], v[8:15], v[24:31], v[116:119]
	v_mfma_f32_16x16x128_f8f6f4 v[104:107], v[0:7], v[32:39], v[104:107]
	v_mfma_f32_16x16x128_f8f6f4 v[108:111], v[8:15], v[32:39], v[108:111]
	v_mfma_f32_16x16x128_f8f6f4 v[88:91], v[0:7], v[144:151], v[88:91]
	v_mfma_f32_16x16x128_f8f6f4 v[92:95], v[8:15], v[144:151], v[92:95]
	v_mfma_f32_16x16x128_f8f6f4 v[96:99], v[128:135], v[16:23], v[96:99]
	v_mfma_f32_16x16x128_f8f6f4 v[100:103], v[136:143], v[16:23], v[100:103]
	v_mfma_f32_16x16x128_f8f6f4 v[80:83], v[128:135], v[24:31], v[80:83]
	v_mfma_f32_16x16x128_f8f6f4 v[84:87], v[136:143], v[24:31], v[84:87]
	v_mfma_f32_16x16x128_f8f6f4 v[72:75], v[128:135], v[32:39], v[72:75]
	v_mfma_f32_16x16x128_f8f6f4 v[76:79], v[136:143], v[32:39], v[76:79]
	v_mfma_f32_16x16x128_f8f6f4 v[64:67], v[128:135], v[144:151], v[64:67]
	v_mfma_f32_16x16x128_f8f6f4 v[68:71], v[136:143], v[144:151], v[68:71]
	s_barrier
	s_setprio 0
	s_add_i32 s36, s42, s48
	v_lshl_add_u64 v[24:25], v[178:179], 0, s[8:9]
	s_mov_b32 m0, s36
	ds_read_b128 v[16:19], v192 offset:49152
	ds_read_b128 v[20:23], v192 offset:50176
	ds_read_b128 v[144:147], v192 offset:51200
	ds_read_b128 v[148:151], v192 offset:52224
	ds_read_b128 v[152:155], v192 offset:53248
	ds_read_b128 v[156:159], v192 offset:54272
	ds_read_b128 v[196:199], v192 offset:55296
	ds_read_b128 v[200:203], v192 offset:56320
	global_load_lds_dwordx4 v[24:25], off sc1
	s_add_i32 m0, s36, 0x2000
	s_add_u32 s34, s34, 0x40080
	v_lshl_add_u64 v[24:25], v[180:181], 0, s[8:9]
	s_addc_u32 s35, s35, 0
	s_add_i32 s36, s43, s48
	global_load_lds_dwordx4 v[24:25], off sc1
	v_lshl_add_u64 v[24:25], s[34:35], 0, v[164:165]
	s_mov_b32 m0, s36
	s_nop 0
	global_load_lds_dwordx4 v[24:25], off sc1
	v_lshl_add_u64 v[24:25], s[34:35], 0, v[160:161]
	s_add_i32 m0, s36, 0x2000
	s_nop 0
	global_load_lds_dwordx4 v[24:25], off sc1
	v_lshl_add_u64 v[24:25], v[182:183], 0, s[8:9]
	s_mov_b32 m0, s70
	s_nop 0
	global_load_lds_dwordx4 v[24:25], off sc1
	v_lshl_add_u64 v[24:25], v[184:185], 0, s[8:9]
	s_mov_b32 m0, s71
	s_nop 0
	global_load_lds_dwordx4 v[24:25], off sc1
	s_setprio 1
	s_waitcnt vmcnt(8) lgkmcnt(0)
	s_barrier
	v_mfma_f32_16x16x128_f8f6f4 v[56:59], v[0:7], v[16:23], v[56:59]
	v_mfma_f32_16x16x128_f8f6f4 v[60:63], v[8:15], v[16:23], v[60:63]
	v_mfma_f32_16x16x128_f8f6f4 v[48:51], v[0:7], v[144:151], v[48:51]
	v_mfma_f32_16x16x128_f8f6f4 v[52:55], v[8:15], v[144:151], v[52:55]
	v_mfma_f32_16x16x128_f8f6f4 v[40:43], v[0:7], v[152:159], v[40:43]
	v_mfma_f32_16x16x128_f8f6f4 v[44:47], v[8:15], v[152:159], v[44:47]
	v_mfma_f32_16x16x128_f8f6f4 v[24:27], v[0:7], v[196:203], v[228:231]
	v_mfma_f32_16x16x128_f8f6f4 v[28:31], v[8:15], v[196:203], v[232:235]
	v_mfma_f32_16x16x128_f8f6f4 v[32:35], v[128:135], v[16:23], v[236:239]
	v_mfma_f32_16x16x128_f8f6f4 v[36:39], v[136:143], v[16:23], v[240:243]
	v_mfma_f32_16x16x128_f8f6f4 v[16:19], v[128:135], v[144:151], v[244:247]
	v_mfma_f32_16x16x128_f8f6f4 v[20:23], v[136:143], v[144:151], v[204:207]
	v_mfma_f32_16x16x128_f8f6f4 v[8:11], v[128:135], v[152:159], v[208:211]
	v_mfma_f32_16x16x128_f8f6f4 v[12:15], v[136:143], v[152:159], v[212:215]
	v_mfma_f32_16x16x128_f8f6f4 v[0:3], v[128:135], v[196:203], v[216:219]
	v_mfma_f32_16x16x128_f8f6f4 v[4:7], v[136:143], v[196:203], v[220:223]
	s_barrier
	s_setprio 0
	s_add_u32 s30, s30, 0x100
	s_addc_u32 s31, s31, 0
	s_add_u32 s87, s87, 0x100
	s_addc_u32 s88, s88, 0
	s_cmp_ge_u32 s3, s83
	s_mov_b32 s34, s3
	s_cbranch_scc0 .LBB0_572
; __device__ __forceinline__ unsigned cvt_pk_bf16(float lo, float hi) { unsigned r; asm volatile("s_nop 1\n\tv_cvt_pk_bf16_f32 %0, %1, %2" : "=v"(r) : "v"(lo), "v"(hi)); return r; }
;     __device__ __forceinline__ void operator()(const Acc& acc, const Unit& u, int wr, int wc, int fr, int fq) const {
;     ...
;                     const size_t ro = (size_t)(ai * HALF + m * 16) * DH;
; #pragma unroll
;                     for (int bj = 0; bj < 2; ++bj) {
;                         const f32x4 v0 = acc[ai][bj][m][0] * QS, v1 = acc[ai][bj][m][1] * QS;
;                         u32x4 w; w.x = cvt_pk_bf16(v0[0], v0[1]); w.y = cvt_pk_bf16(v0[2], v0[3]); w.z = cvt_pk_bf16(v1[0], v1[1]); w.w = cvt_pk_bf16(v1[2], v1[3]);
; template <class Epi, bool ALIGN_EPI = true, bool FP8 = false>
; __device__ __forceinline__ void gemm_phase(LAS unsigned char* lds, const Gemm g, const StaticOrder& S, const Epi& E, const int wid) {
;     ...
;         if constexpr (FP8) {
; #pragma unroll
;             for (int a = 0; a < 2; ++a)
; #pragma unroll
;                 for (int b = 0; b < 2; ++b)
; #pragma unroll
;                     for (int m = 0; m < 4; ++m) { const f32x8 c_ = acc8[a][b][m]; acc[a][b][m][0] = __builtin_shufflevector(c_, c_, 0, 1, 2, 3); acc[a][b][m][1] = __builtin_shufflevector(c_, c_, 4, 5, 6, 7); }
;         }
	v_pk_mul_f32 v[122:123], v[122:123], s[14:15] op_sel_hi:[1,0]
	v_pk_mul_f32 v[128:129], v[120:121], s[14:15] op_sel_hi:[1,0]
	v_pk_mul_f32 v[120:121], v[126:127], s[14:15] op_sel_hi:[1,0]
	v_pk_mul_f32 v[124:125], v[124:125], s[14:15] op_sel_hi:[1,0]
	v_pk_mul_f32 v[132:133], v[98:99], s[14:15] op_sel_hi:[1,0]
	v_pk_mul_f32 v[136:137], v[96:97], s[14:15] op_sel_hi:[1,0]
	v_pk_mul_f32 v[130:131], v[102:103], s[14:15] op_sel_hi:[1,0]
	v_pk_mul_f32 v[134:135], v[100:101], s[14:15] op_sel_hi:[1,0]
	v_pk_mul_f32 v[100:101], v[114:115], s[14:15] op_sel_hi:[1,0]
	v_pk_mul_f32 v[112:113], v[112:113], s[14:15] op_sel_hi:[1,0]
	v_pk_mul_f32 v[96:97], v[118:119], s[14:15] op_sel_hi:[1,0]
	v_pk_mul_f32 v[102:103], v[116:117], s[14:15] op_sel_hi:[1,0]
	v_pk_mul_f32 v[116:117], v[82:83], s[14:15] op_sel_hi:[1,0]
	v_pk_mul_f32 v[126:127], v[80:81], s[14:15] op_sel_hi:[1,0]
	v_pk_mul_f32 v[114:115], v[86:87], s[14:15] op_sel_hi:[1,0]
	v_pk_mul_f32 v[118:119], v[84:85], s[14:15] op_sel_hi:[1,0]
	v_pk_mul_f32 v[82:83], v[106:107], s[14:15] op_sel_hi:[1,0]
	v_pk_mul_f32 v[86:87], v[104:105], s[14:15] op_sel_hi:[1,0]
	v_pk_mul_f32 v[80:81], v[110:111], s[14:15] op_sel_hi:[1,0]
	v_pk_mul_f32 v[84:85], v[108:109], s[14:15] op_sel_hi:[1,0]
	v_pk_mul_f32 v[104:105], v[74:75], s[14:15] op_sel_hi:[1,0]
	v_pk_mul_f32 v[108:109], v[72:73], s[14:15] op_sel_hi:[1,0]
	v_pk_mul_f32 v[98:99], v[78:79], s[14:15] op_sel_hi:[1,0]
	v_pk_mul_f32 v[106:107], v[76:77], s[14:15] op_sel_hi:[1,0]
	v_pk_mul_f32 v[74:75], v[90:91], s[14:15] op_sel_hi:[1,0]
	v_pk_mul_f32 v[78:79], v[88:89], s[14:15] op_sel_hi:[1,0]
	v_pk_mul_f32 v[72:73], v[94:95], s[14:15] op_sel_hi:[1,0]
	v_pk_mul_f32 v[76:77], v[92:93], s[14:15] op_sel_hi:[1,0]
	v_pk_mul_f32 v[66:67], v[66:67], s[14:15] op_sel_hi:[1,0]
	v_pk_mul_f32 v[88:89], v[64:65], s[14:15] op_sel_hi:[1,0]
	v_pk_mul_f32 v[64:65], v[70:71], s[14:15] op_sel_hi:[1,0]
	v_pk_mul_f32 v[68:69], v[68:69], s[14:15] op_sel_hi:[1,0]
	v_pk_mul_f32 v[58:59], v[58:59], s[14:15] op_sel_hi:[1,0]
	v_pk_mul_f32 v[70:71], v[56:57], s[14:15] op_sel_hi:[1,0]
	v_pk_mul_f32 v[56:57], v[62:63], s[14:15] op_sel_hi:[1,0]
	v_pk_mul_f32 v[60:61], v[60:61], s[14:15] op_sel_hi:[1,0]
	v_pk_mul_f32 v[92:93], v[34:35], s[14:15] op_sel_hi:[1,0]
	v_pk_mul_f32 v[110:111], v[32:33], s[14:15] op_sel_hi:[1,0]
	v_pk_mul_f32 v[90:91], v[38:39], s[14:15] op_sel_hi:[1,0]
	v_pk_mul_f32 v[94:95], v[36:37], s[14:15] op_sel_hi:[1,0]
	v_pk_mul_f32 v[36:37], v[50:51], s[14:15] op_sel_hi:[1,0]
	v_pk_mul_f32 v[48:49], v[48:49], s[14:15] op_sel_hi:[1,0]
	v_pk_mul_f32 v[32:33], v[54:55], s[14:15] op_sel_hi:[1,0]
	v_pk_mul_f32 v[38:39], v[52:53], s[14:15] op_sel_hi:[1,0]
	v_pk_mul_f32 v[52:53], v[18:19], s[14:15] op_sel_hi:[1,0]
	v_pk_mul_f32 v[62:63], v[16:17], s[14:15] op_sel_hi:[1,0]
	v_pk_mul_f32 v[50:51], v[22:23], s[14:15] op_sel_hi:[1,0]
	v_pk_mul_f32 v[54:55], v[20:21], s[14:15] op_sel_hi:[1,0]
	v_pk_mul_f32 v[18:19], v[42:43], s[14:15] op_sel_hi:[1,0]
	v_pk_mul_f32 v[22:23], v[40:41], s[14:15] op_sel_hi:[1,0]
	v_pk_mul_f32 v[16:17], v[46:47], s[14:15] op_sel_hi:[1,0]
	v_pk_mul_f32 v[20:21], v[44:45], s[14:15] op_sel_hi:[1,0]
	v_pk_mul_f32 v[40:41], v[10:11], s[14:15] op_sel_hi:[1,0]
	v_pk_mul_f32 v[44:45], v[8:9], s[14:15] op_sel_hi:[1,0]
	v_pk_mul_f32 v[34:35], v[14:15], s[14:15] op_sel_hi:[1,0]
	v_pk_mul_f32 v[42:43], v[12:13], s[14:15] op_sel_hi:[1,0]
	v_pk_mul_f32 v[10:11], v[26:27], s[14:15] op_sel_hi:[1,0]
	v_pk_mul_f32 v[14:15], v[24:25], s[14:15] op_sel_hi:[1,0]
	v_pk_mul_f32 v[8:9], v[30:31], s[14:15] op_sel_hi:[1,0]
	v_pk_mul_f32 v[12:13], v[28:29], s[14:15] op_sel_hi:[1,0]
	v_pk_mul_f32 v[2:3], v[2:3], s[14:15] op_sel_hi:[1,0]
	v_pk_mul_f32 v[24:25], v[0:1], s[14:15] op_sel_hi:[1,0]
	v_pk_mul_f32 v[0:1], v[6:7], s[14:15] op_sel_hi:[1,0]
	v_pk_mul_f32 v[4:5], v[4:5], s[14:15] op_sel_hi:[1,0]
	s_and_b64 vcc, exec, s[12:13]
	s_cbranch_vccz .LBB0_575

; #define PG8_STAGE(bufoff, gbase, voff) do { _Pragma("unroll") for (int _i = 0; _i < 2; ++_i) \
;         __builtin_amdgcn_global_load_lds((const unsigned*)((const char*)(gbase) + (voff)[_i]), (LAS unsigned*)(lds + (bufoff) + ldsw + _i * 8192), 16, 0, 0); } while (0)
; #define PG8_LDA(dst, b, h) do { _Pragma("unroll") for (int m = 0; m < 4; ++m) _Pragma("unroll") for (int k = 0; k < 2; ++k) dst[m][k] = *(const LAS bf16x8*)(lds + PG8_SA(b, h) + aoff + m * 2048 + k * KOFF); } while (0)
; #define PG8_LDB(dst, b, h) do { _Pragma("unroll") for (int n = 0; n < 2; ++n) _Pragma("unroll") for (int k = 0; k < 2; ++k) dst[n][k] = *(const LAS bf16x8*)(lds + PG8_SB(b, h) + boff + n * 2048 + k * KOFF); } while (0)
; #define PG8_WAIT_V(n) asm volatile("s_waitcnt vmcnt(" #n ")" ::: "memory")
; #define PG8_WAIT_L(n) asm volatile("s_waitcnt lgkmcnt(" #n ")" ::: "memory")
; #define PG8_BAR __builtin_amdgcn_s_barrier()
; #define PG8_SCHED __builtin_amdgcn_sched_barrier(0)
; template <class Epi, bool ALIGN_EPI = true, bool FP8 = false>
; __device__ __forceinline__ void gemm_phase(LAS unsigned char* lds, const Gemm g, const StaticOrder& S, const Epi& E, const int wid) {
;     ...
;             const char* a1 = cA + (size_t)(t + 1) * kstep;
;             const char* a2 = last ? nA : cA + (size_t)(t + 2) * kstep; const char* b2 = last ? nB : cB + (size_t)(t + 2) * kstep;
;             const char* a3 = a2 + kstep; const char* b3 = b2 + kstep;
;             PG8_LDB(B0, 0, 0); PG8_LDB(B1, 0, 1); PG8_SCHED; PG8_LDA(At, 0, 0); PG8_STAGE(PG8_SA(1, 1), a1 + hstep, voffA);
;             PG8_WAIT_V(8); PG8_WAIT_L(0); PG8_BAR; PG8_MMA(0, 0, At, B0); PG8_MMA(0, 1, At, B1); PG8_BAR; PG8_SCHED;
;             PG8_LDA(At, 0, 1); PG8_STAGE(PG8_SB(0, 0), b2, voffB); PG8_STAGE(PG8_SB(0, 1), b2 + hstep, voffB); PG8_STAGE(PG8_SA(0, 0), a2, voffA);
;             PG8_WAIT_V(8); PG8_WAIT_L(0); PG8_BAR; PG8_MMA(1, 0, At, B0); PG8_MMA(1, 1, At, B1); PG8_BAR; PG8_SCHED;
.LBB0_2058:
	v_add_u32_e32 v128, s83, v192
	v_add_u32_e32 v132, s84, v192
	ds_read_b128 v[152:155], v128
	ds_read_b128 v[156:159], v128 offset:1024
	ds_read_b128 v[144:147], v128 offset:2048
	ds_read_b128 v[148:151], v128 offset:3072
	ds_read_b128 v[136:139], v132
	ds_read_b128 v[140:143], v132 offset:1024
	ds_read_b128 v[128:131], v132 offset:2048
	ds_read_b128 v[132:135], v132 offset:3072
	s_add_i32 s3, s42, 2
	s_add_u32 s43, s64, 0xfffe0080
	s_addc_u32 s52, s65, -1
	s_cmp_eq_u32 s35, s42
	s_cselect_b32 s69, s11, s52
	s_cselect_b32 s68, s16, s43
	s_cselect_b32 s67, s29, s90
	s_cselect_b32 s66, s31, s89
	v_lshl_add_u64 v[188:189], s[64:65], 0, v[174:175]
	s_add_i32 m0, s72, 0xc000
	ds_read_b128 v[180:183], v193
	ds_read_b128 v[184:187], v193 offset:1024
	ds_read_b128 v[196:199], v193 offset:2048
	ds_read_b128 v[200:203], v193 offset:3072
	ds_read_b128 v[204:207], v193 offset:4096
	ds_read_b128 v[208:211], v193 offset:5120
	ds_read_b128 v[212:215], v193 offset:6144
	ds_read_b128 v[216:219], v193 offset:7168
	global_load_lds_dwordx4 v[188:189], off sc1
	v_lshl_add_u64 v[188:189], s[64:65], 0, v[176:177]
	s_add_i32 m0, s72, 0xe000
	s_nop 0
	global_load_lds_dwordx4 v[188:189], off sc1
	s_setprio 1
	s_waitcnt vmcnt(8) lgkmcnt(0)
	s_barrier
	v_mfma_f32_16x16x128_f8f6f4 v[120:123], v[152:159], v[180:187], v[120:123]
	v_mfma_f32_16x16x128_f8f6f4 v[124:127], v[144:151], v[180:187], v[124:127]
	v_mfma_f32_16x16x128_f8f6f4 v[112:115], v[152:159], v[196:203], v[112:115]
	v_mfma_f32_16x16x128_f8f6f4 v[116:119], v[144:151], v[196:203], v[116:119]
	v_mfma_f32_16x16x128_f8f6f4 v[104:107], v[152:159], v[204:211], v[104:107]
	v_mfma_f32_16x16x128_f8f6f4 v[108:111], v[144:151], v[204:211], v[108:111]
	v_mfma_f32_16x16x128_f8f6f4 v[96:99], v[152:159], v[212:219], v[96:99]
	v_mfma_f32_16x16x128_f8f6f4 v[100:103], v[144:151], v[212:219], v[100:103]
	v_mfma_f32_16x16x128_f8f6f4 v[88:91], v[136:143], v[180:187], v[88:91]
	v_mfma_f32_16x16x128_f8f6f4 v[92:95], v[128:135], v[180:187], v[92:95]
	v_mfma_f32_16x16x128_f8f6f4 v[80:83], v[136:143], v[196:203], v[80:83]
	v_mfma_f32_16x16x128_f8f6f4 v[84:87], v[128:135], v[196:203], v[84:87]
	v_mfma_f32_16x16x128_f8f6f4 v[72:75], v[136:143], v[204:211], v[72:75]
	v_mfma_f32_16x16x128_f8f6f4 v[76:79], v[128:135], v[204:211], v[76:79]
	v_mfma_f32_16x16x128_f8f6f4 v[64:67], v[136:143], v[212:219], v[64:67]
	v_mfma_f32_16x16x128_f8f6f4 v[68:71], v[128:135], v[212:219], v[68:71]
	s_barrier
	s_setprio 0
	s_add_i32 s42, s83, s71
	v_lshl_add_u64 v[180:181], s[66:67], 0, v[162:163]
	s_mov_b32 m0, s42
	ds_read_b128 v[196:199], v193 offset:16384
	ds_read_b128 v[200:203], v193 offset:17408
	ds_read_b128 v[204:207], v193 offset:18432
	ds_read_b128 v[208:211], v193 offset:19456
	ds_read_b128 v[212:215], v193 offset:20480
	ds_read_b128 v[216:219], v193 offset:21504
	ds_read_b128 v[220:223], v193 offset:22528
	ds_read_b128 v[224:227], v193 offset:23552
	global_load_lds_dwordx4 v[180:181], off sc1
	s_add_i32 m0, s42, 0x2000
	s_add_u32 s42, s66, 0x20000
	v_lshl_add_u64 v[182:183], s[66:67], 0, v[166:167]
	s_addc_u32 s43, s67, 0
	s_add_i32 s52, s84, s71
	global_load_lds_dwordx4 v[182:183], off sc1
	v_lshl_add_u64 v[184:185], s[42:43], 0, v[162:163]
	s_mov_b32 m0, s52
	v_lshl_add_u64 v[186:187], s[68:69], 0, v[164:165]
	global_load_lds_dwordx4 v[184:185], off sc1
	v_lshl_add_u64 v[184:185], s[42:43], 0, v[166:167]
	s_add_i32 m0, s52, 0x2000
	s_nop 0
	global_load_lds_dwordx4 v[184:185], off sc1
	v_lshl_add_u64 v[184:185], s[68:69], 0, v[160:161]
	s_mov_b32 m0, s72
	s_nop 0
	global_load_lds_dwordx4 v[184:185], off sc1
	s_mov_b32 m0, s73
	s_nop 0
	global_load_lds_dwordx4 v[186:187], off sc1
	s_setprio 1
	s_waitcnt vmcnt(8) lgkmcnt(0)
	s_barrier
	v_mfma_f32_16x16x128_f8f6f4 v[56:59], v[152:159], v[196:203], v[56:59]
	v_mfma_f32_16x16x128_f8f6f4 v[60:63], v[144:151], v[196:203], v[60:63]
	v_mfma_f32_16x16x128_f8f6f4 v[48:51], v[152:159], v[204:211], v[48:51]
	v_mfma_f32_16x16x128_f8f6f4 v[52:55], v[144:151], v[204:211], v[52:55]
	v_mfma_f32_16x16x128_f8f6f4 v[40:43], v[152:159], v[212:219], v[40:43]
	v_mfma_f32_16x16x128_f8f6f4 v[44:47], v[144:151], v[212:219], v[44:47]
	v_mfma_f32_16x16x128_f8f6f4 v[188:191], v[152:159], v[220:227], v[32:35]
	v_mfma_f32_16x16x128_f8f6f4 v[228:231], v[144:151], v[220:227], v[36:39]
	v_mfma_f32_16x16x128_f8f6f4 v[232:235], v[136:143], v[196:203], v[24:27]
	v_mfma_f32_16x16x128_f8f6f4 v[236:239], v[128:135], v[196:203], v[28:31]
	v_mfma_f32_16x16x128_f8f6f4 v[240:243], v[136:143], v[204:211], v[16:19]
	v_mfma_f32_16x16x128_f8f6f4 v[204:207], v[128:135], v[204:211], v[20:23]
	v_mfma_f32_16x16x128_f8f6f4 v[208:211], v[136:143], v[212:219], v[8:11]
	v_mfma_f32_16x16x128_f8f6f4 v[212:215], v[128:135], v[212:219], v[12:15]
	v_mfma_f32_16x16x128_f8f6f4 v[216:219], v[136:143], v[220:227], v[0:3]
	v_mfma_f32_16x16x128_f8f6f4 v[220:223], v[128:135], v[220:227], v[4:7]
	s_barrier
; #define PG8_STAGE(bufoff, gbase, voff) do { _Pragma("unroll") for (int _i = 0; _i < 2; ++_i) \
;         __builtin_amdgcn_global_load_lds((const unsigned*)((const char*)(gbase) + (voff)[_i]), (LAS unsigned*)(lds + (bufoff) + ldsw + _i * 8192), 16, 0, 0); } while (0)
; #define PG8_LDA(dst, b, h) do { _Pragma("unroll") for (int m = 0; m < 4; ++m) _Pragma("unroll") for (int k = 0; k < 2; ++k) dst[m][k] = *(const LAS bf16x8*)(lds + PG8_SA(b, h) + aoff + m * 2048 + k * KOFF); } while (0)
; #define PG8_LDB(dst, b, h) do { _Pragma("unroll") for (int n = 0; n < 2; ++n) _Pragma("unroll") for (int k = 0; k < 2; ++k) dst[n][k] = *(const LAS bf16x8*)(lds + PG8_SB(b, h) + boff + n * 2048 + k * KOFF); } while (0)
; #define PG8_WAIT_V(n) asm volatile("s_waitcnt vmcnt(" #n ")" ::: "memory")
; #define PG8_WAIT_L(n) asm volatile("s_waitcnt lgkmcnt(" #n ")" ::: "memory")
; #define PG8_BAR __builtin_amdgcn_s_barrier()
; #define PG8_SCHED __builtin_amdgcn_sched_barrier(0)
; template <class Epi, bool ALIGN_EPI = true, bool FP8 = false>
; __device__ __forceinline__ void gemm_phase(LAS unsigned char* lds, const Gemm g, const StaticOrder& S, const Epi& E, const int wid) {
;     ...
;             PG8_LDB(B0, 1, 0); PG8_LDB(B1, 1, 1); PG8_SCHED; PG8_LDA(At, 1, 0); PG8_STAGE(PG8_SA(0, 1), a2 + hstep, voffA);
;             PG8_WAIT_V(8); PG8_WAIT_L(0); PG8_BAR; PG8_MMA(0, 0, At, B0); PG8_MMA(0, 1, At, B1); PG8_BAR; PG8_SCHED;
;             PG8_LDA(At, 1, 1); PG8_STAGE(PG8_SB(1, 0), b3, voffB); PG8_STAGE(PG8_SB(1, 1), b3 + hstep, voffB); PG8_STAGE(PG8_SA(1, 0), a3, voffA);
;             PG8_WAIT_V(8); PG8_WAIT_L(0); PG8_BAR; PG8_MMA(1, 0, At, B0); PG8_MMA(1, 1, At, B1); PG8_BAR; PG8_SCHED;
;         }
	s_setprio 0
	s_add_i32 s52, 0, 0x18000
	s_add_i32 s54, 0, 0x1c000
	s_nop 0
	v_add_u32_e32 v12, s52, v192
	v_add_u32_e32 v16, s54, v192
	ds_read_b128 v[0:3], v12
	ds_read_b128 v[4:7], v12 offset:1024
	ds_read_b128 v[8:11], v12 offset:2048
	ds_read_b128 v[12:15], v12 offset:3072
	ds_read_b128 v[128:131], v16
	ds_read_b128 v[132:135], v16 offset:1024
	ds_read_b128 v[136:139], v16 offset:2048
	ds_read_b128 v[140:143], v16 offset:3072
	s_add_u32 s42, s68, 0x20000
	s_addc_u32 s43, s69, 0
	s_mov_b32 m0, s74
	v_lshl_add_u64 v[152:153], s[42:43], 0, v[160:161]
	ds_read_b128 v[16:19], v193 offset:32768
	ds_read_b128 v[20:23], v193 offset:33792
	ds_read_b128 v[24:27], v193 offset:34816
	ds_read_b128 v[28:31], v193 offset:35840
	ds_read_b128 v[32:35], v193 offset:36864
	ds_read_b128 v[36:39], v193 offset:37888
	ds_read_b128 v[144:147], v193 offset:38912
	ds_read_b128 v[148:151], v193 offset:39936
	global_load_lds_dwordx4 v[152:153], off sc1
	v_lshl_add_u64 v[152:153], s[42:43], 0, v[164:165]
	s_mov_b32 m0, s75
	s_nop 0
	global_load_lds_dwordx4 v[152:153], off sc1
	s_setprio 1
	s_waitcnt vmcnt(8) lgkmcnt(0)
	s_barrier
	v_mfma_f32_16x16x128_f8f6f4 v[120:123], v[0:7], v[16:23], v[120:123]
	v_mfma_f32_16x16x128_f8f6f4 v[124:127], v[8:15], v[16:23], v[124:127]
	v_mfma_f32_16x16x128_f8f6f4 v[112:115], v[0:7], v[24:31], v[112:115]
	v_mfma_f32_16x16x128_f8f6f4 v[116:119], v[8:15], v[24:31], v[116:119]
	v_mfma_f32_16x16x128_f8f6f4 v[104:107], v[0:7], v[32:39], v[104:107]
	v_mfma_f32_16x16x128_f8f6f4 v[108:111], v[8:15], v[32:39], v[108:111]
	v_mfma_f32_16x16x128_f8f6f4 v[96:99], v[0:7], v[144:151], v[96:99]
	v_mfma_f32_16x16x128_f8f6f4 v[100:103], v[8:15], v[144:151], v[100:103]
	v_mfma_f32_16x16x128_f8f6f4 v[88:91], v[128:135], v[16:23], v[88:91]
	v_mfma_f32_16x16x128_f8f6f4 v[92:95], v[136:143], v[16:23], v[92:95]
	v_mfma_f32_16x16x128_f8f6f4 v[80:83], v[128:135], v[24:31], v[80:83]
	v_mfma_f32_16x16x128_f8f6f4 v[84:87], v[136:143], v[24:31], v[84:87]
	v_mfma_f32_16x16x128_f8f6f4 v[72:75], v[128:135], v[32:39], v[72:75]
	v_mfma_f32_16x16x128_f8f6f4 v[76:79], v[136:143], v[32:39], v[76:79]
	v_mfma_f32_16x16x128_f8f6f4 v[64:67], v[128:135], v[144:151], v[64:67]
	v_mfma_f32_16x16x128_f8f6f4 v[68:71], v[136:143], v[144:151], v[68:71]
	s_barrier
	s_setprio 0
	s_add_i32 s42, s52, s71
	v_lshl_add_u64 v[24:25], v[180:181], 0, s[20:21]
	s_mov_b32 m0, s42
	ds_read_b128 v[16:19], v193 offset:49152
	ds_read_b128 v[20:23], v193 offset:50176
	ds_read_b128 v[144:147], v193 offset:51200
	ds_read_b128 v[148:151], v193 offset:52224
	ds_read_b128 v[152:155], v193 offset:53248
	ds_read_b128 v[156:159], v193 offset:54272
	ds_read_b128 v[196:199], v193 offset:55296
	ds_read_b128 v[200:203], v193 offset:56320
	global_load_lds_dwordx4 v[24:25], off sc1
	s_add_i32 m0, s42, 0x2000
	s_add_u32 s42, s66, 0x20080
	v_lshl_add_u64 v[24:25], v[182:183], 0, s[20:21]
	s_addc_u32 s43, s67, 0
	s_add_i32 s52, s54, s71
	global_load_lds_dwordx4 v[24:25], off sc1
	v_lshl_add_u64 v[24:25], s[42:43], 0, v[162:163]
	s_mov_b32 m0, s52
	s_nop 0
	global_load_lds_dwordx4 v[24:25], off sc1
	v_lshl_add_u64 v[24:25], s[42:43], 0, v[166:167]
	s_add_i32 m0, s52, 0x2000
	s_nop 0
	global_load_lds_dwordx4 v[24:25], off sc1
	v_lshl_add_u64 v[24:25], v[184:185], 0, s[20:21]
	s_mov_b32 m0, s80
	s_nop 0
	global_load_lds_dwordx4 v[24:25], off sc1
	v_lshl_add_u64 v[24:25], v[186:187], 0, s[20:21]
	s_mov_b32 m0, s81
	s_nop 0
	global_load_lds_dwordx4 v[24:25], off sc1
	s_setprio 1
	s_waitcnt vmcnt(8) lgkmcnt(0)
	s_barrier
	v_mfma_f32_16x16x128_f8f6f4 v[56:59], v[0:7], v[16:23], v[56:59]
	v_mfma_f32_16x16x128_f8f6f4 v[60:63], v[8:15], v[16:23], v[60:63]
	v_mfma_f32_16x16x128_f8f6f4 v[48:51], v[0:7], v[144:151], v[48:51]
	v_mfma_f32_16x16x128_f8f6f4 v[52:55], v[8:15], v[144:151], v[52:55]
	v_mfma_f32_16x16x128_f8f6f4 v[40:43], v[0:7], v[152:159], v[40:43]
	v_mfma_f32_16x16x128_f8f6f4 v[44:47], v[8:15], v[152:159], v[44:47]
	v_mfma_f32_16x16x128_f8f6f4 v[32:35], v[0:7], v[196:203], v[188:191]
	v_mfma_f32_16x16x128_f8f6f4 v[36:39], v[8:15], v[196:203], v[228:231]
	v_mfma_f32_16x16x128_f8f6f4 v[24:27], v[128:135], v[16:23], v[232:235]
	v_mfma_f32_16x16x128_f8f6f4 v[28:31], v[136:143], v[16:23], v[236:239]
	v_mfma_f32_16x16x128_f8f6f4 v[16:19], v[128:135], v[144:151], v[240:243]
	v_mfma_f32_16x16x128_f8f6f4 v[20:23], v[136:143], v[144:151], v[204:207]
	v_mfma_f32_16x16x128_f8f6f4 v[8:11], v[128:135], v[152:159], v[208:211]
	v_mfma_f32_16x16x128_f8f6f4 v[12:15], v[136:143], v[152:159], v[212:215]
	v_mfma_f32_16x16x128_f8f6f4 v[0:3], v[128:135], v[196:203], v[216:219]
	v_mfma_f32_16x16x128_f8f6f4 v[4:7], v[136:143], v[196:203], v[220:223]
	s_barrier
	s_setprio 0
	s_add_u32 s64, s64, 0x100
	s_addc_u32 s65, s65, 0
	s_add_u32 s89, s89, 0x100
	s_addc_u32 s90, s90, 0
	s_cmp_ge_u32 s3, s9
	s_mov_b32 s42, s3
	s_cbranch_scc0 .LBB0_2058
	s_and_b64 vcc, exec, s[22:23]
	s_cbranch_vccz .LBB0_2061
	s_barrier

; #define PG8_STAGE(bufoff, gbase, voff) do { _Pragma("unroll") for (int _i = 0; _i < 2; ++_i) \
;         __builtin_amdgcn_global_load_lds((const unsigned*)((const char*)(gbase) + (voff)[_i]), (LAS unsigned*)(lds + (bufoff) + ldsw + _i * 8192), 16, 0, 0); } while (0)
; #define PG8_LDA(dst, b, h) do { _Pragma("unroll") for (int m = 0; m < 4; ++m) _Pragma("unroll") for (int k = 0; k < 2; ++k) dst[m][k] = *(const LAS bf16x8*)(lds + PG8_SA(b, h) + aoff + m * 2048 + k * KOFF); } while (0)
; #define PG8_LDB(dst, b, h) do { _Pragma("unroll") for (int n = 0; n < 2; ++n) _Pragma("unroll") for (int k = 0; k < 2; ++k) dst[n][k] = *(const LAS bf16x8*)(lds + PG8_SB(b, h) + boff + n * 2048 + k * KOFF); } while (0)
; #define PG8_WAIT_V(n) asm volatile("s_waitcnt vmcnt(" #n ")" ::: "memory")
; #define PG8_WAIT_L(n) asm volatile("s_waitcnt lgkmcnt(" #n ")" ::: "memory")
; #define PG8_BAR __builtin_amdgcn_s_barrier()
; #define PG8_SCHED __builtin_amdgcn_sched_barrier(0)
; template <class Epi, bool ALIGN_EPI = true, bool FP8 = false>
; __device__ __forceinline__ void gemm_phase(LAS unsigned char* lds, const Gemm g, const StaticOrder& S, const Epi& E, const int wid) {
;     ...
;             const char* a1 = cA + (size_t)(t + 1) * kstep;
;             const char* a2 = last ? nA : cA + (size_t)(t + 2) * kstep; const char* b2 = last ? nB : cB + (size_t)(t + 2) * kstep;
;             const char* a3 = a2 + kstep; const char* b3 = b2 + kstep;
;             PG8_LDB(B0, 0, 0); PG8_LDB(B1, 0, 1); PG8_SCHED; PG8_LDA(At, 0, 0); PG8_STAGE(PG8_SA(1, 1), a1 + hstep, voffA);
;             PG8_WAIT_V(8); PG8_WAIT_L(0); PG8_BAR; PG8_MMA(0, 0, At, B0); PG8_MMA(0, 1, At, B1); PG8_BAR; PG8_SCHED;
;             PG8_LDA(At, 0, 1); PG8_STAGE(PG8_SB(0, 0), b2, voffB); PG8_STAGE(PG8_SB(0, 1), b2 + hstep, voffB); PG8_STAGE(PG8_SA(0, 0), a2, voffA);
;             PG8_WAIT_V(8); PG8_WAIT_L(0); PG8_BAR; PG8_MMA(1, 0, At, B0); PG8_MMA(1, 1, At, B1); PG8_BAR; PG8_SCHED;
.LBB0_2290:
	ds_read_b128 v[152:155], v218
	ds_read_b128 v[156:159], v218 offset:1024
	ds_read_b128 v[144:147], v218 offset:2048
	ds_read_b128 v[148:151], v218 offset:3072
	ds_read_b128 v[136:139], v219
	ds_read_b128 v[140:143], v219 offset:1024
	ds_read_b128 v[128:131], v219 offset:2048
	ds_read_b128 v[132:135], v219 offset:3072
	s_add_i32 s3, s38, 2
	s_add_u32 s36, s34, 0xfffc0080
	s_addc_u32 s37, s35, -1
	s_cmp_eq_u32 s88, s38
	s_cselect_b32 s38, s31, s36
	s_cselect_b32 s39, s21, s37
	s_cselect_b32 s37, s19, s90
	s_cselect_b32 s36, s87, s89
	v_lshl_add_u64 v[212:213], s[34:35], 0, v[198:199]
	s_add_i32 m0, s27, 0xc000
	ds_read_b128 v[160:163], v220
	ds_read_b128 v[164:167], v220 offset:1024
	ds_read_b128 v[168:171], v220 offset:2048
	ds_read_b128 v[172:175], v220 offset:3072
	ds_read_b128 v[176:179], v220 offset:4096
	ds_read_b128 v[180:183], v220 offset:5120
	ds_read_b128 v[204:207], v220 offset:6144
	ds_read_b128 v[208:211], v220 offset:7168
	global_load_lds_dwordx4 v[212:213], off sc1
	v_lshl_add_u64 v[212:213], s[34:35], 0, v[200:201]
	s_add_i32 m0, s27, 0xe000
	s_nop 0
	global_load_lds_dwordx4 v[212:213], off sc1
	s_setprio 1
	s_waitcnt vmcnt(8) lgkmcnt(0)
	s_barrier
	v_mfma_f32_16x16x128_f8f6f4 v[120:123], v[152:159], v[160:167], v[120:123]
	v_mfma_f32_16x16x128_f8f6f4 v[124:127], v[144:151], v[160:167], v[124:127]
	v_mfma_f32_16x16x128_f8f6f4 v[104:107], v[152:159], v[168:175], v[104:107]
	v_mfma_f32_16x16x128_f8f6f4 v[108:111], v[144:151], v[168:175], v[108:111]
	v_mfma_f32_16x16x128_f8f6f4 v[96:99], v[152:159], v[176:183], v[96:99]
	v_mfma_f32_16x16x128_f8f6f4 v[100:103], v[144:151], v[176:183], v[100:103]
	v_mfma_f32_16x16x128_f8f6f4 v[80:83], v[152:159], v[204:211], v[80:83]
	v_mfma_f32_16x16x128_f8f6f4 v[84:87], v[144:151], v[204:211], v[84:87]
	v_mfma_f32_16x16x128_f8f6f4 v[112:115], v[136:143], v[160:167], v[112:115]
	v_mfma_f32_16x16x128_f8f6f4 v[116:119], v[128:135], v[160:167], v[116:119]
	v_mfma_f32_16x16x128_f8f6f4 v[88:91], v[136:143], v[168:175], v[88:91]
	v_mfma_f32_16x16x128_f8f6f4 v[92:95], v[128:135], v[168:175], v[92:95]
	v_mfma_f32_16x16x128_f8f6f4 v[72:75], v[136:143], v[176:183], v[72:75]
	v_mfma_f32_16x16x128_f8f6f4 v[76:79], v[128:135], v[176:183], v[76:79]
	v_mfma_f32_16x16x128_f8f6f4 v[64:67], v[136:143], v[204:211], v[64:67]
	v_mfma_f32_16x16x128_f8f6f4 v[68:71], v[128:135], v[204:211], v[68:71]
	s_barrier
	s_setprio 0
	s_add_i32 s42, s75, s53
	v_lshl_add_u64 v[160:161], s[36:37], 0, v[188:189]
	s_mov_b32 m0, s42
	ds_read_b128 v[168:171], v220 offset:16384
	ds_read_b128 v[172:175], v220 offset:17408
	ds_read_b128 v[176:179], v220 offset:18432
	ds_read_b128 v[180:183], v220 offset:19456
	ds_read_b128 v[204:207], v220 offset:20480
	ds_read_b128 v[208:211], v220 offset:21504
	ds_read_b128 v[222:225], v220 offset:22528
	ds_read_b128 v[226:229], v220 offset:23552
	global_load_lds_dwordx4 v[160:161], off sc1
	s_add_i32 m0, s42, 0x2000
	s_add_u32 s42, s36, 0x40000
	v_lshl_add_u64 v[162:163], s[36:37], 0, v[184:185]
	s_addc_u32 s43, s37, 0
	s_add_i32 s52, s76, s53
	global_load_lds_dwordx4 v[162:163], off sc1
	v_lshl_add_u64 v[164:165], s[42:43], 0, v[188:189]
	s_mov_b32 m0, s52
	v_lshl_add_u64 v[166:167], s[38:39], 0, v[186:187]
	global_load_lds_dwordx4 v[164:165], off sc1
	v_lshl_add_u64 v[164:165], s[42:43], 0, v[184:185]
	s_add_i32 m0, s52, 0x2000
	s_nop 0
	global_load_lds_dwordx4 v[164:165], off sc1
	v_lshl_add_u64 v[164:165], s[38:39], 0, v[190:191]
	s_mov_b32 m0, s27
	s_nop 0
	global_load_lds_dwordx4 v[164:165], off sc1
	s_mov_b32 m0, s55
	s_nop 0
	global_load_lds_dwordx4 v[166:167], off sc1
	s_setprio 1
	s_waitcnt vmcnt(8) lgkmcnt(0)
	s_barrier
	v_mfma_f32_16x16x128_f8f6f4 v[56:59], v[152:159], v[168:175], v[56:59]
	v_mfma_f32_16x16x128_f8f6f4 v[60:63], v[144:151], v[168:175], v[60:63]
	v_mfma_f32_16x16x128_f8f6f4 v[48:51], v[152:159], v[176:183], v[48:51]
	v_mfma_f32_16x16x128_f8f6f4 v[52:55], v[144:151], v[176:183], v[52:55]
	v_mfma_f32_16x16x128_f8f6f4 v[32:35], v[152:159], v[204:211], v[32:35]
	v_mfma_f32_16x16x128_f8f6f4 v[212:215], v[144:151], v[204:211], v[36:39]
	v_mfma_f32_16x16x128_f8f6f4 v[230:233], v[152:159], v[222:229], v[16:19]
	v_mfma_f32_16x16x128_f8f6f4 v[234:237], v[144:151], v[222:229], v[20:23]
	v_mfma_f32_16x16x128_f8f6f4 v[44:47], v[128:135], v[168:175], v[44:47]
	v_mfma_f32_16x16x128_f8f6f4 v[238:241], v[136:143], v[168:175], v[40:43]
	v_mfma_f32_16x16x128_f8f6f4 v[242:245], v[136:143], v[176:183], v[24:27]
	v_mfma_f32_16x16x128_f8f6f4 v[176:179], v[128:135], v[176:183], v[28:31]
	v_mfma_f32_16x16x128_f8f6f4 v[180:183], v[136:143], v[204:211], v[8:11]
	v_mfma_f32_16x16x128_f8f6f4 v[204:207], v[128:135], v[204:211], v[12:15]
	v_mfma_f32_16x16x128_f8f6f4 v[208:211], v[136:143], v[222:229], v[0:3]
	v_mfma_f32_16x16x128_f8f6f4 v[222:225], v[128:135], v[222:229], v[4:7]
	s_barrier
; #define PG8_STAGE(bufoff, gbase, voff) do { _Pragma("unroll") for (int _i = 0; _i < 2; ++_i) \
;         __builtin_amdgcn_global_load_lds((const unsigned*)((const char*)(gbase) + (voff)[_i]), (LAS unsigned*)(lds + (bufoff) + ldsw + _i * 8192), 16, 0, 0); } while (0)
; #define PG8_LDA(dst, b, h) do { _Pragma("unroll") for (int m = 0; m < 4; ++m) _Pragma("unroll") for (int k = 0; k < 2; ++k) dst[m][k] = *(const LAS bf16x8*)(lds + PG8_SA(b, h) + aoff + m * 2048 + k * KOFF); } while (0)
; #define PG8_LDB(dst, b, h) do { _Pragma("unroll") for (int n = 0; n < 2; ++n) _Pragma("unroll") for (int k = 0; k < 2; ++k) dst[n][k] = *(const LAS bf16x8*)(lds + PG8_SB(b, h) + boff + n * 2048 + k * KOFF); } while (0)
; #define PG8_WAIT_V(n) asm volatile("s_waitcnt vmcnt(" #n ")" ::: "memory")
; #define PG8_WAIT_L(n) asm volatile("s_waitcnt lgkmcnt(" #n ")" ::: "memory")
; #define PG8_BAR __builtin_amdgcn_s_barrier()
; #define PG8_SCHED __builtin_amdgcn_sched_barrier(0)
; template <class Epi, bool ALIGN_EPI = true, bool FP8 = false>
; __device__ __forceinline__ void gemm_phase(LAS unsigned char* lds, const Gemm g, const StaticOrder& S, const Epi& E, const int wid) {
;     ...
;             PG8_LDB(B0, 1, 0); PG8_LDB(B1, 1, 1); PG8_SCHED; PG8_LDA(At, 1, 0); PG8_STAGE(PG8_SA(0, 1), a2 + hstep, voffA);
;             PG8_WAIT_V(8); PG8_WAIT_L(0); PG8_BAR; PG8_MMA(0, 0, At, B0); PG8_MMA(0, 1, At, B1); PG8_BAR; PG8_SCHED;
;             PG8_LDA(At, 1, 1); PG8_STAGE(PG8_SB(1, 0), b3, voffB); PG8_STAGE(PG8_SB(1, 1), b3 + hstep, voffB); PG8_STAGE(PG8_SA(1, 0), a3, voffA);
;             PG8_WAIT_V(8); PG8_WAIT_L(0); PG8_BAR; PG8_MMA(1, 0, At, B0); PG8_MMA(1, 1, At, B1); PG8_BAR; PG8_SCHED;
;         }
	s_setprio 0
	s_add_i32 s42, 0, 0x18000
	s_add_i32 s43, 0, 0x1c000
	s_nop 0
	v_add_u32_e32 v12, s42, v217
	v_add_u32_e32 v16, s43, v217
	ds_read_b128 v[0:3], v12
	ds_read_b128 v[4:7], v12 offset:1024
	ds_read_b128 v[8:11], v12 offset:2048
	ds_read_b128 v[12:15], v12 offset:3072
	ds_read_b128 v[128:131], v16
	ds_read_b128 v[132:135], v16 offset:1024
	ds_read_b128 v[136:139], v16 offset:2048
	ds_read_b128 v[140:143], v16 offset:3072
	s_add_u32 s38, s38, 0x40000
	s_addc_u32 s39, s39, 0
	s_mov_b32 m0, s64
	v_lshl_add_u64 v[152:153], s[38:39], 0, v[190:191]
	ds_read_b128 v[16:19], v220 offset:32768
	ds_read_b128 v[20:23], v220 offset:33792
	ds_read_b128 v[24:27], v220 offset:34816
	ds_read_b128 v[28:31], v220 offset:35840
	ds_read_b128 v[36:39], v220 offset:36864
	ds_read_b128 v[40:43], v220 offset:37888
	ds_read_b128 v[144:147], v220 offset:38912
	ds_read_b128 v[148:151], v220 offset:39936
	global_load_lds_dwordx4 v[152:153], off sc1
	v_lshl_add_u64 v[152:153], s[38:39], 0, v[186:187]
	s_mov_b32 m0, s65
	s_nop 0
	global_load_lds_dwordx4 v[152:153], off sc1
	s_setprio 1
	s_waitcnt vmcnt(8) lgkmcnt(0)
	s_barrier
	v_mfma_f32_16x16x128_f8f6f4 v[120:123], v[0:7], v[16:23], v[120:123]
	v_mfma_f32_16x16x128_f8f6f4 v[124:127], v[8:15], v[16:23], v[124:127]
	v_mfma_f32_16x16x128_f8f6f4 v[104:107], v[0:7], v[24:31], v[104:107]
	v_mfma_f32_16x16x128_f8f6f4 v[108:111], v[8:15], v[24:31], v[108:111]
	v_mfma_f32_16x16x128_f8f6f4 v[96:99], v[0:7], v[36:43], v[96:99]
	v_mfma_f32_16x16x128_f8f6f4 v[100:103], v[8:15], v[36:43], v[100:103]
	v_mfma_f32_16x16x128_f8f6f4 v[80:83], v[0:7], v[144:151], v[80:83]
	v_mfma_f32_16x16x128_f8f6f4 v[84:87], v[8:15], v[144:151], v[84:87]
	v_mfma_f32_16x16x128_f8f6f4 v[112:115], v[128:135], v[16:23], v[112:115]
	v_mfma_f32_16x16x128_f8f6f4 v[116:119], v[136:143], v[16:23], v[116:119]
	v_mfma_f32_16x16x128_f8f6f4 v[88:91], v[128:135], v[24:31], v[88:91]
	v_mfma_f32_16x16x128_f8f6f4 v[92:95], v[136:143], v[24:31], v[92:95]
	v_mfma_f32_16x16x128_f8f6f4 v[72:75], v[128:135], v[36:43], v[72:75]
	v_mfma_f32_16x16x128_f8f6f4 v[76:79], v[136:143], v[36:43], v[76:79]
	v_mfma_f32_16x16x128_f8f6f4 v[64:67], v[128:135], v[144:151], v[64:67]
	v_mfma_f32_16x16x128_f8f6f4 v[68:71], v[136:143], v[144:151], v[68:71]
	s_barrier
	s_setprio 0
	s_add_i32 s38, s42, s53
	v_lshl_add_u64 v[16:17], v[160:161], 0, s[14:15]
	s_mov_b32 m0, s38
	ds_read_b128 v[24:27], v220 offset:49152
	ds_read_b128 v[28:31], v220 offset:50176
	ds_read_b128 v[144:147], v220 offset:51200
	ds_read_b128 v[148:151], v220 offset:52224
	ds_read_b128 v[152:155], v220 offset:53248
	ds_read_b128 v[156:159], v220 offset:54272
	ds_read_b128 v[168:171], v220 offset:55296
	ds_read_b128 v[172:175], v220 offset:56320
	global_load_lds_dwordx4 v[16:17], off sc1
	s_add_i32 m0, s38, 0x2000
	s_add_u32 s36, s36, 0x40080
	v_lshl_add_u64 v[16:17], v[162:163], 0, s[14:15]
	s_addc_u32 s37, s37, 0
	s_add_i32 s38, s43, s53
	global_load_lds_dwordx4 v[16:17], off sc1
	v_lshl_add_u64 v[16:17], s[36:37], 0, v[188:189]
	s_mov_b32 m0, s38
	s_nop 0
	global_load_lds_dwordx4 v[16:17], off sc1
	v_lshl_add_u64 v[16:17], s[36:37], 0, v[184:185]
	s_add_i32 m0, s38, 0x2000
	s_nop 0
	global_load_lds_dwordx4 v[16:17], off sc1
	v_lshl_add_u64 v[16:17], v[164:165], 0, s[14:15]
	s_mov_b32 m0, s71
	s_nop 0
	global_load_lds_dwordx4 v[16:17], off sc1
	v_lshl_add_u64 v[16:17], v[166:167], 0, s[14:15]
	s_mov_b32 m0, s72
	s_nop 0
	global_load_lds_dwordx4 v[16:17], off sc1
	s_setprio 1
	s_waitcnt vmcnt(8) lgkmcnt(0)
	s_barrier
	v_mfma_f32_16x16x128_f8f6f4 v[56:59], v[0:7], v[24:31], v[56:59]
	v_mfma_f32_16x16x128_f8f6f4 v[60:63], v[8:15], v[24:31], v[60:63]
	v_mfma_f32_16x16x128_f8f6f4 v[48:51], v[0:7], v[144:151], v[48:51]
	v_mfma_f32_16x16x128_f8f6f4 v[52:55], v[8:15], v[144:151], v[52:55]
	v_mfma_f32_16x16x128_f8f6f4 v[32:35], v[0:7], v[152:159], v[32:35]
	v_mfma_f32_16x16x128_f8f6f4 v[36:39], v[8:15], v[152:159], v[212:215]
	v_mfma_f32_16x16x128_f8f6f4 v[16:19], v[0:7], v[168:175], v[230:233]
	v_mfma_f32_16x16x128_f8f6f4 v[20:23], v[8:15], v[168:175], v[234:237]
	v_mfma_f32_16x16x128_f8f6f4 v[40:43], v[128:135], v[24:31], v[238:241]
	v_mfma_f32_16x16x128_f8f6f4 v[44:47], v[136:143], v[24:31], v[44:47]
	v_mfma_f32_16x16x128_f8f6f4 v[24:27], v[128:135], v[144:151], v[242:245]
	v_mfma_f32_16x16x128_f8f6f4 v[28:31], v[136:143], v[144:151], v[176:179]
	v_mfma_f32_16x16x128_f8f6f4 v[8:11], v[128:135], v[152:159], v[180:183]
	v_mfma_f32_16x16x128_f8f6f4 v[12:15], v[136:143], v[152:159], v[204:207]
	v_mfma_f32_16x16x128_f8f6f4 v[0:3], v[128:135], v[168:175], v[208:211]
	v_mfma_f32_16x16x128_f8f6f4 v[4:7], v[136:143], v[168:175], v[222:225]
	s_barrier
	s_setprio 0
	s_add_u32 s34, s34, 0x100
	s_addc_u32 s35, s35, 0
	s_add_u32 s89, s89, 0x100
	s_addc_u32 s90, s90, 0
	s_cmp_ge_u32 s3, s29
	s_mov_b32 s38, s3
	s_cbranch_scc0 .LBB0_2290
	s_and_b64 vcc, exec, s[12:13]
	s_cbranch_vccz .LBB0_2293
	s_barrier

; #define PG8_STAGE(bufoff, gbase, voff) do { _Pragma("unroll") for (int _i = 0; _i < 2; ++_i) \
;         __builtin_amdgcn_global_load_lds((const unsigned*)((const char*)(gbase) + (voff)[_i]), (LAS unsigned*)(lds + (bufoff) + ldsw + _i * 8192), 16, 0, 0); } while (0)
; #define PG8_LDA(dst, b, h) do { _Pragma("unroll") for (int m = 0; m < 4; ++m) _Pragma("unroll") for (int k = 0; k < 2; ++k) dst[m][k] = *(const LAS bf16x8*)(lds + PG8_SA(b, h) + aoff + m * 2048 + k * KOFF); } while (0)
; #define PG8_LDB(dst, b, h) do { _Pragma("unroll") for (int n = 0; n < 2; ++n) _Pragma("unroll") for (int k = 0; k < 2; ++k) dst[n][k] = *(const LAS bf16x8*)(lds + PG8_SB(b, h) + boff + n * 2048 + k * KOFF); } while (0)
; #define PG8_WAIT_V(n) asm volatile("s_waitcnt vmcnt(" #n ")" ::: "memory")
; #define PG8_WAIT_L(n) asm volatile("s_waitcnt lgkmcnt(" #n ")" ::: "memory")
; #define PG8_BAR __builtin_amdgcn_s_barrier()
; #define PG8_SCHED __builtin_amdgcn_sched_barrier(0)
; template <class Epi, bool ALIGN_EPI = true, bool FP8 = false>
; __device__ __forceinline__ void gemm_phase(LAS unsigned char* lds, const Gemm g, const StaticOrder& S, const Epi& E, const int wid) {
;     ...
;             const char* a1 = cA + (size_t)(t + 1) * kstep;
;             const char* a2 = last ? nA : cA + (size_t)(t + 2) * kstep; const char* b2 = last ? nB : cB + (size_t)(t + 2) * kstep;
;             const char* a3 = a2 + kstep; const char* b3 = b2 + kstep;
;             PG8_LDB(B0, 0, 0); PG8_LDB(B1, 0, 1); PG8_SCHED; PG8_LDA(At, 0, 0); PG8_STAGE(PG8_SA(1, 1), a1 + hstep, voffA);
;             PG8_WAIT_V(8); PG8_WAIT_L(0); PG8_BAR; PG8_MMA(0, 0, At, B0); PG8_MMA(0, 1, At, B1); PG8_BAR; PG8_SCHED;
;             PG8_LDA(At, 0, 1); PG8_STAGE(PG8_SB(0, 0), b2, voffB); PG8_STAGE(PG8_SB(0, 1), b2 + hstep, voffB); PG8_STAGE(PG8_SA(0, 0), a2, voffA);
;             PG8_WAIT_V(8); PG8_WAIT_L(0); PG8_BAR; PG8_MMA(1, 0, At, B0); PG8_MMA(1, 1, At, B1); PG8_BAR; PG8_SCHED;
.LBB0_2452:
	ds_read_b128 v[152:155], v148
	ds_read_b128 v[156:159], v148 offset:1024
	ds_read_b128 v[160:163], v148 offset:2048
	ds_read_b128 v[164:167], v148 offset:3072
	ds_read_b128 v[168:171], v149
	ds_read_b128 v[172:175], v149 offset:1024
	ds_read_b128 v[176:179], v149 offset:2048
	ds_read_b128 v[180:183], v149 offset:3072
	s_add_i32 s76, s30, 2
	s_add_u32 s31, s28, 0xfff80080
	s_addc_u32 s34, s29, -1
	s_cmp_eq_u32 s43, s30
	s_cselect_b32 s30, s42, s52
	s_cselect_b32 s35, s3, s34
	s_cselect_b32 s34, s17, s31
	s_cselect_b32 s31, s19, s75
	v_lshl_add_u64 v[144:145], s[28:29], 0, v[138:139]
	s_add_i32 m0, s25, 0xc000
	ds_read_b128 v[184:187], v150
	ds_read_b128 v[188:191], v150 offset:1024
	ds_read_b128 v[192:195], v150 offset:2048
	ds_read_b128 v[196:199], v150 offset:3072
	ds_read_b128 v[200:203], v150 offset:4096
	ds_read_b128 v[204:207], v150 offset:5120
	ds_read_b128 v[208:211], v150 offset:6144
	ds_read_b128 v[212:215], v150 offset:7168
	global_load_lds_dwordx4 v[144:145], off sc1
	v_lshl_add_u64 v[144:145], s[28:29], 0, v[140:141]
	s_add_i32 m0, s25, 0xe000
	s_nop 0
	global_load_lds_dwordx4 v[144:145], off sc1
	s_setprio 1
	s_waitcnt vmcnt(8) lgkmcnt(0)
	s_barrier
	v_mfma_f32_16x16x32_bf16 v[124:127], v[152:155], v[184:187], v[124:127]
	v_mfma_f32_16x16x32_bf16 v[116:119], v[160:163], v[184:187], v[116:119]
	v_mfma_f32_16x16x32_bf16 v[108:111], v[152:155], v[192:195], v[108:111]
	v_mfma_f32_16x16x32_bf16 v[100:103], v[160:163], v[192:195], v[100:103]
	v_mfma_f32_16x16x32_bf16 v[92:95], v[152:155], v[200:203], v[92:95]
	v_mfma_f32_16x16x32_bf16 v[84:87], v[160:163], v[200:203], v[84:87]
	v_mfma_f32_16x16x32_bf16 v[76:79], v[152:155], v[208:211], v[76:79]
	v_mfma_f32_16x16x32_bf16 v[68:71], v[160:163], v[208:211], v[68:71]
	v_mfma_f32_16x16x32_bf16 v[124:127], v[156:159], v[188:191], v[124:127]
	v_mfma_f32_16x16x32_bf16 v[116:119], v[164:167], v[188:191], v[116:119]
	v_mfma_f32_16x16x32_bf16 v[108:111], v[156:159], v[196:199], v[108:111]
	v_mfma_f32_16x16x32_bf16 v[100:103], v[164:167], v[196:199], v[100:103]
	v_mfma_f32_16x16x32_bf16 v[92:95], v[156:159], v[204:207], v[92:95]
	v_mfma_f32_16x16x32_bf16 v[84:87], v[164:167], v[204:207], v[84:87]
	v_mfma_f32_16x16x32_bf16 v[76:79], v[156:159], v[212:215], v[76:79]
	v_mfma_f32_16x16x32_bf16 v[68:71], v[164:167], v[212:215], v[68:71]
	v_mfma_f32_16x16x32_bf16 v[120:123], v[168:171], v[184:187], v[120:123]
	v_mfma_f32_16x16x32_bf16 v[112:115], v[176:179], v[184:187], v[112:115]
	v_mfma_f32_16x16x32_bf16 v[104:107], v[168:171], v[192:195], v[104:107]
	v_mfma_f32_16x16x32_bf16 v[96:99], v[176:179], v[192:195], v[96:99]
	v_mfma_f32_16x16x32_bf16 v[88:91], v[168:171], v[200:203], v[88:91]
	v_mfma_f32_16x16x32_bf16 v[80:83], v[176:179], v[200:203], v[80:83]
	v_mfma_f32_16x16x32_bf16 v[72:75], v[168:171], v[208:211], v[72:75]
	v_mfma_f32_16x16x32_bf16 v[64:67], v[176:179], v[208:211], v[64:67]
	v_mfma_f32_16x16x32_bf16 v[120:123], v[172:175], v[188:191], v[120:123]
	v_mfma_f32_16x16x32_bf16 v[112:115], v[180:183], v[188:191], v[112:115]
	v_mfma_f32_16x16x32_bf16 v[104:107], v[172:175], v[196:199], v[104:107]
	v_mfma_f32_16x16x32_bf16 v[96:99], v[180:183], v[196:199], v[96:99]
	v_mfma_f32_16x16x32_bf16 v[88:91], v[172:175], v[204:207], v[88:91]
	v_mfma_f32_16x16x32_bf16 v[80:83], v[180:183], v[204:207], v[80:83]
	v_mfma_f32_16x16x32_bf16 v[72:75], v[172:175], v[212:215], v[72:75]
	v_mfma_f32_16x16x32_bf16 v[64:67], v[180:183], v[212:215], v[64:67]
	s_barrier
	s_setprio 0
	s_add_i32 s77, s65, s38
	v_lshl_add_u64 v[144:145], s[30:31], 0, v[132:133]
	s_mov_b32 m0, s77
	ds_read_b128 v[184:187], v150 offset:16384
	ds_read_b128 v[188:191], v150 offset:17408
	ds_read_b128 v[192:195], v150 offset:18432
	ds_read_b128 v[196:199], v150 offset:19456
	ds_read_b128 v[200:203], v150 offset:20480
	ds_read_b128 v[204:207], v150 offset:21504
	ds_read_b128 v[208:211], v150 offset:22528
	ds_read_b128 v[212:215], v150 offset:23552
	global_load_lds_dwordx4 v[144:145], off sc1
	s_add_i32 m0, s77, 0x2000
	s_add_u32 s78, s30, 0x80000
	v_lshl_add_u64 v[216:217], s[30:31], 0, v[128:129]
	s_addc_u32 s79, s31, 0
	s_add_i32 s77, s66, s38
	global_load_lds_dwordx4 v[216:217], off sc1
	v_lshl_add_u64 v[218:219], s[78:79], 0, v[132:133]
	s_mov_b32 m0, s77
	v_lshl_add_u64 v[220:221], s[34:35], 0, v[130:131]
	global_load_lds_dwordx4 v[218:219], off sc1
	v_lshl_add_u64 v[218:219], s[78:79], 0, v[128:129]
	s_add_i32 m0, s77, 0x2000
	s_nop 0
	global_load_lds_dwordx4 v[218:219], off sc1
	v_lshl_add_u64 v[218:219], s[34:35], 0, v[134:135]
	s_mov_b32 m0, s25
	s_nop 0
	global_load_lds_dwordx4 v[218:219], off sc1
	s_mov_b32 m0, s27
	s_nop 0
	global_load_lds_dwordx4 v[220:221], off sc1
	s_setprio 1
	s_waitcnt vmcnt(8) lgkmcnt(0)
	s_barrier
; #define PG8_STAGE(bufoff, gbase, voff) do { _Pragma("unroll") for (int _i = 0; _i < 2; ++_i) \
;         __builtin_amdgcn_global_load_lds((const unsigned*)((const char*)(gbase) + (voff)[_i]), (LAS unsigned*)(lds + (bufoff) + ldsw + _i * 8192), 16, 0, 0); } while (0)
; #define PG8_LDA(dst, b, h) do { _Pragma("unroll") for (int m = 0; m < 4; ++m) _Pragma("unroll") for (int k = 0; k < 2; ++k) dst[m][k] = *(const LAS bf16x8*)(lds + PG8_SA(b, h) + aoff + m * 2048 + k * KOFF); } while (0)
; #define PG8_LDB(dst, b, h) do { _Pragma("unroll") for (int n = 0; n < 2; ++n) _Pragma("unroll") for (int k = 0; k < 2; ++k) dst[n][k] = *(const LAS bf16x8*)(lds + PG8_SB(b, h) + boff + n * 2048 + k * KOFF); } while (0)
; #define PG8_WAIT_V(n) asm volatile("s_waitcnt vmcnt(" #n ")" ::: "memory")
; #define PG8_WAIT_L(n) asm volatile("s_waitcnt lgkmcnt(" #n ")" ::: "memory")
; #define PG8_BAR __builtin_amdgcn_s_barrier()
; #define PG8_SCHED __builtin_amdgcn_sched_barrier(0)
; template <class Epi, bool ALIGN_EPI = true, bool FP8 = false>
; __device__ __forceinline__ void gemm_phase(LAS unsigned char* lds, const Gemm g, const StaticOrder& S, const Epi& E, const int wid) {
;     ...
;             PG8_LDB(B0, 1, 0); PG8_LDB(B1, 1, 1); PG8_SCHED; PG8_LDA(At, 1, 0); PG8_STAGE(PG8_SA(0, 1), a2 + hstep, voffA);
;             PG8_WAIT_V(8); PG8_WAIT_L(0); PG8_BAR; PG8_MMA(0, 0, At, B0); PG8_MMA(0, 1, At, B1); PG8_BAR; PG8_SCHED;
;             PG8_LDA(At, 1, 1); PG8_STAGE(PG8_SB(1, 0), b3, voffB); PG8_STAGE(PG8_SB(1, 1), b3 + hstep, voffB); PG8_STAGE(PG8_SA(1, 0), a3, voffA);
;             PG8_WAIT_V(8); PG8_WAIT_L(0); PG8_BAR; PG8_MMA(1, 0, At, B0); PG8_MMA(1, 1, At, B1); PG8_BAR; PG8_SCHED;
	v_mfma_f32_16x16x32_bf16 v[60:63], v[152:155], v[184:187], v[60:63]
	v_mfma_f32_16x16x32_bf16 v[52:55], v[160:163], v[184:187], v[52:55]
	v_mfma_f32_16x16x32_bf16 v[44:47], v[152:155], v[192:195], v[44:47]
	v_mfma_f32_16x16x32_bf16 v[36:39], v[160:163], v[192:195], v[36:39]
	v_mfma_f32_16x16x32_bf16 v[28:31], v[152:155], v[200:203], v[28:31]
	v_mfma_f32_16x16x32_bf16 v[20:23], v[160:163], v[200:203], v[20:23]
	v_mfma_f32_16x16x32_bf16 v[12:15], v[152:155], v[208:211], v[12:15]
	v_mfma_f32_16x16x32_bf16 v[4:7], v[160:163], v[208:211], v[4:7]
	v_mfma_f32_16x16x32_bf16 v[60:63], v[156:159], v[188:191], v[60:63]
	v_mfma_f32_16x16x32_bf16 v[52:55], v[164:167], v[188:191], v[52:55]
	v_mfma_f32_16x16x32_bf16 v[44:47], v[156:159], v[196:199], v[44:47]
	v_mfma_f32_16x16x32_bf16 v[36:39], v[164:167], v[196:199], v[36:39]
	v_mfma_f32_16x16x32_bf16 v[28:31], v[156:159], v[204:207], v[28:31]
	v_mfma_f32_16x16x32_bf16 v[20:23], v[164:167], v[204:207], v[20:23]
	v_mfma_f32_16x16x32_bf16 v[12:15], v[156:159], v[212:215], v[12:15]
	v_mfma_f32_16x16x32_bf16 v[4:7], v[164:167], v[212:215], v[4:7]
	v_mfma_f32_16x16x32_bf16 v[56:59], v[168:171], v[184:187], v[56:59]
	v_mfma_f32_16x16x32_bf16 v[48:51], v[176:179], v[184:187], v[48:51]
	v_mfma_f32_16x16x32_bf16 v[40:43], v[168:171], v[192:195], v[40:43]
	v_mfma_f32_16x16x32_bf16 v[32:35], v[176:179], v[192:195], v[32:35]
	v_mfma_f32_16x16x32_bf16 v[24:27], v[168:171], v[200:203], v[24:27]
	v_mfma_f32_16x16x32_bf16 v[16:19], v[176:179], v[200:203], v[16:19]
	v_mfma_f32_16x16x32_bf16 v[8:11], v[168:171], v[208:211], v[8:11]
	v_mfma_f32_16x16x32_bf16 v[0:3], v[176:179], v[208:211], v[0:3]
	v_mfma_f32_16x16x32_bf16 v[56:59], v[172:175], v[188:191], v[56:59]
	v_mfma_f32_16x16x32_bf16 v[48:51], v[180:183], v[188:191], v[48:51]
	v_mfma_f32_16x16x32_bf16 v[40:43], v[172:175], v[196:199], v[40:43]
	v_mfma_f32_16x16x32_bf16 v[32:35], v[180:183], v[196:199], v[32:35]
	v_mfma_f32_16x16x32_bf16 v[24:27], v[172:175], v[204:207], v[24:27]
	v_mfma_f32_16x16x32_bf16 v[16:19], v[180:183], v[204:207], v[16:19]
	v_mfma_f32_16x16x32_bf16 v[8:11], v[172:175], v[212:215], v[8:11]
	v_mfma_f32_16x16x32_bf16 v[0:3], v[180:183], v[212:215], v[0:3]
	s_barrier
	s_setprio 0
	s_add_i32 s77, 0, 0x18000
	s_add_i32 s78, 0, 0x1c000
	v_add_u32_e32 v164, s77, v147
	v_add_u32_e32 v180, s78, v147
	ds_read_b128 v[152:155], v164
	ds_read_b128 v[156:159], v164 offset:1024
	ds_read_b128 v[160:163], v164 offset:2048
	ds_read_b128 v[164:167], v164 offset:3072
	ds_read_b128 v[168:171], v180
	ds_read_b128 v[172:175], v180 offset:1024
	ds_read_b128 v[176:179], v180 offset:2048
	ds_read_b128 v[180:183], v180 offset:3072
	s_add_u32 s34, s34, 0x80000
	s_addc_u32 s35, s35, 0
	s_mov_b32 m0, s39
	v_lshl_add_u64 v[222:223], s[34:35], 0, v[134:135]
	ds_read_b128 v[184:187], v150 offset:32768
	ds_read_b128 v[188:191], v150 offset:33792
	ds_read_b128 v[192:195], v150 offset:34816
	ds_read_b128 v[196:199], v150 offset:35840
	ds_read_b128 v[200:203], v150 offset:36864
	ds_read_b128 v[204:207], v150 offset:37888
	ds_read_b128 v[208:211], v150 offset:38912
	ds_read_b128 v[212:215], v150 offset:39936
	global_load_lds_dwordx4 v[222:223], off sc1
	v_lshl_add_u64 v[222:223], s[34:35], 0, v[130:131]
	s_mov_b32 m0, s48
	s_nop 0
	global_load_lds_dwordx4 v[222:223], off sc1
	s_setprio 1
	s_waitcnt vmcnt(8) lgkmcnt(0)
	s_barrier
	v_mfma_f32_16x16x32_bf16 v[124:127], v[152:155], v[184:187], v[124:127]
	v_mfma_f32_16x16x32_bf16 v[116:119], v[160:163], v[184:187], v[116:119]
	v_mfma_f32_16x16x32_bf16 v[108:111], v[152:155], v[192:195], v[108:111]
	v_mfma_f32_16x16x32_bf16 v[100:103], v[160:163], v[192:195], v[100:103]
	v_mfma_f32_16x16x32_bf16 v[92:95], v[152:155], v[200:203], v[92:95]
	v_mfma_f32_16x16x32_bf16 v[84:87], v[160:163], v[200:203], v[84:87]
	v_mfma_f32_16x16x32_bf16 v[76:79], v[152:155], v[208:211], v[76:79]
	v_mfma_f32_16x16x32_bf16 v[68:71], v[160:163], v[208:211], v[68:71]
	v_mfma_f32_16x16x32_bf16 v[124:127], v[156:159], v[188:191], v[124:127]
	v_mfma_f32_16x16x32_bf16 v[116:119], v[164:167], v[188:191], v[116:119]
	v_mfma_f32_16x16x32_bf16 v[108:111], v[156:159], v[196:199], v[108:111]
	v_mfma_f32_16x16x32_bf16 v[100:103], v[164:167], v[196:199], v[100:103]
	v_mfma_f32_16x16x32_bf16 v[92:95], v[156:159], v[204:207], v[92:95]
	v_mfma_f32_16x16x32_bf16 v[84:87], v[164:167], v[204:207], v[84:87]
	v_mfma_f32_16x16x32_bf16 v[76:79], v[156:159], v[212:215], v[76:79]
	v_mfma_f32_16x16x32_bf16 v[68:71], v[164:167], v[212:215], v[68:71]
	v_mfma_f32_16x16x32_bf16 v[120:123], v[168:171], v[184:187], v[120:123]
	v_mfma_f32_16x16x32_bf16 v[112:115], v[176:179], v[184:187], v[112:115]
	v_mfma_f32_16x16x32_bf16 v[104:107], v[168:171], v[192:195], v[104:107]
	v_mfma_f32_16x16x32_bf16 v[96:99], v[176:179], v[192:195], v[96:99]
	v_mfma_f32_16x16x32_bf16 v[88:91], v[168:171], v[200:203], v[88:91]
	v_mfma_f32_16x16x32_bf16 v[80:83], v[176:179], v[200:203], v[80:83]
	v_mfma_f32_16x16x32_bf16 v[72:75], v[168:171], v[208:211], v[72:75]
	v_mfma_f32_16x16x32_bf16 v[64:67], v[176:179], v[208:211], v[64:67]
	v_mfma_f32_16x16x32_bf16 v[120:123], v[172:175], v[188:191], v[120:123]
	v_mfma_f32_16x16x32_bf16 v[112:115], v[180:183], v[188:191], v[112:115]
	v_mfma_f32_16x16x32_bf16 v[104:107], v[172:175], v[196:199], v[104:107]
	v_mfma_f32_16x16x32_bf16 v[96:99], v[180:183], v[196:199], v[96:99]
	v_mfma_f32_16x16x32_bf16 v[88:91], v[172:175], v[204:207], v[88:91]
	v_mfma_f32_16x16x32_bf16 v[80:83], v[180:183], v[204:207], v[80:83]
	v_mfma_f32_16x16x32_bf16 v[72:75], v[172:175], v[212:215], v[72:75]
	v_mfma_f32_16x16x32_bf16 v[64:67], v[180:183], v[212:215], v[64:67]
	s_barrier
; #define PG8_STAGE(bufoff, gbase, voff) do { _Pragma("unroll") for (int _i = 0; _i < 2; ++_i) \
;         __builtin_amdgcn_global_load_lds((const unsigned*)((const char*)(gbase) + (voff)[_i]), (LAS unsigned*)(lds + (bufoff) + ldsw + _i * 8192), 16, 0, 0); } while (0)
; #define PG8_LDA(dst, b, h) do { _Pragma("unroll") for (int m = 0; m < 4; ++m) _Pragma("unroll") for (int k = 0; k < 2; ++k) dst[m][k] = *(const LAS bf16x8*)(lds + PG8_SA(b, h) + aoff + m * 2048 + k * KOFF); } while (0)
; #define PG8_WAIT_V(n) asm volatile("s_waitcnt vmcnt(" #n ")" ::: "memory")
; #define PG8_WAIT_L(n) asm volatile("s_waitcnt lgkmcnt(" #n ")" ::: "memory")
; #define PG8_BAR __builtin_amdgcn_s_barrier()
; #define PG8_SCHED __builtin_amdgcn_sched_barrier(0)
; template <class Epi, bool ALIGN_EPI = true, bool FP8 = false>
; __device__ __forceinline__ void gemm_phase(LAS unsigned char* lds, const Gemm g, const StaticOrder& S, const Epi& E, const int wid) {
;     ...
;             PG8_LDA(At, 1, 1); PG8_STAGE(PG8_SB(1, 0), b3, voffB); PG8_STAGE(PG8_SB(1, 1), b3 + hstep, voffB); PG8_STAGE(PG8_SA(1, 0), a3, voffA);
;             PG8_WAIT_V(8); PG8_WAIT_L(0); PG8_BAR; PG8_MMA(1, 0, At, B0); PG8_MMA(1, 1, At, B1); PG8_BAR; PG8_SCHED;
;         }
	s_setprio 0
	s_add_i32 s34, s77, s38
	v_lshl_add_u64 v[144:145], v[144:145], 0, s[14:15]
	s_mov_b32 m0, s34
	ds_read_b128 v[184:187], v150 offset:49152
	ds_read_b128 v[188:191], v150 offset:50176
	ds_read_b128 v[192:195], v150 offset:51200
	ds_read_b128 v[196:199], v150 offset:52224
	ds_read_b128 v[200:203], v150 offset:53248
	ds_read_b128 v[204:207], v150 offset:54272
	ds_read_b128 v[208:211], v150 offset:55296
	ds_read_b128 v[212:215], v150 offset:56320
	global_load_lds_dwordx4 v[144:145], off sc1
	s_add_i32 m0, s34, 0x2000
	s_add_u32 s30, s30, 0x80080
	v_lshl_add_u64 v[144:145], v[216:217], 0, s[14:15]
	s_addc_u32 s31, s31, 0
	s_add_i32 s34, s78, s38
	global_load_lds_dwordx4 v[144:145], off sc1
	v_lshl_add_u64 v[144:145], s[30:31], 0, v[132:133]
	s_mov_b32 m0, s34
	s_nop 0
	global_load_lds_dwordx4 v[144:145], off sc1
	v_lshl_add_u64 v[144:145], s[30:31], 0, v[128:129]
	s_add_i32 m0, s34, 0x2000
	s_nop 0
	global_load_lds_dwordx4 v[144:145], off sc1
	v_lshl_add_u64 v[144:145], v[218:219], 0, s[14:15]
	s_mov_b32 m0, s53
	s_nop 0
	global_load_lds_dwordx4 v[144:145], off sc1
	v_lshl_add_u64 v[144:145], v[220:221], 0, s[14:15]
	s_mov_b32 m0, s55
	s_nop 0
	global_load_lds_dwordx4 v[144:145], off sc1
	s_setprio 1
	s_waitcnt vmcnt(8) lgkmcnt(0)
	s_barrier
	v_mfma_f32_16x16x32_bf16 v[60:63], v[152:155], v[184:187], v[60:63]
	v_mfma_f32_16x16x32_bf16 v[52:55], v[160:163], v[184:187], v[52:55]
	v_mfma_f32_16x16x32_bf16 v[44:47], v[152:155], v[192:195], v[44:47]
	v_mfma_f32_16x16x32_bf16 v[36:39], v[160:163], v[192:195], v[36:39]
	v_mfma_f32_16x16x32_bf16 v[28:31], v[152:155], v[200:203], v[28:31]
	v_mfma_f32_16x16x32_bf16 v[20:23], v[160:163], v[200:203], v[20:23]
	v_mfma_f32_16x16x32_bf16 v[12:15], v[152:155], v[208:211], v[12:15]
	v_mfma_f32_16x16x32_bf16 v[4:7], v[160:163], v[208:211], v[4:7]
	v_mfma_f32_16x16x32_bf16 v[60:63], v[156:159], v[188:191], v[60:63]
	v_mfma_f32_16x16x32_bf16 v[52:55], v[164:167], v[188:191], v[52:55]
	v_mfma_f32_16x16x32_bf16 v[44:47], v[156:159], v[196:199], v[44:47]
	v_mfma_f32_16x16x32_bf16 v[36:39], v[164:167], v[196:199], v[36:39]
	v_mfma_f32_16x16x32_bf16 v[28:31], v[156:159], v[204:207], v[28:31]
	v_mfma_f32_16x16x32_bf16 v[20:23], v[164:167], v[204:207], v[20:23]
	v_mfma_f32_16x16x32_bf16 v[12:15], v[156:159], v[212:215], v[12:15]
	v_mfma_f32_16x16x32_bf16 v[4:7], v[164:167], v[212:215], v[4:7]
	v_mfma_f32_16x16x32_bf16 v[56:59], v[168:171], v[184:187], v[56:59]
	v_mfma_f32_16x16x32_bf16 v[48:51], v[176:179], v[184:187], v[48:51]
	v_mfma_f32_16x16x32_bf16 v[40:43], v[168:171], v[192:195], v[40:43]
	v_mfma_f32_16x16x32_bf16 v[32:35], v[176:179], v[192:195], v[32:35]
	v_mfma_f32_16x16x32_bf16 v[24:27], v[168:171], v[200:203], v[24:27]
	v_mfma_f32_16x16x32_bf16 v[16:19], v[176:179], v[200:203], v[16:19]
	v_mfma_f32_16x16x32_bf16 v[8:11], v[168:171], v[208:211], v[8:11]
	v_mfma_f32_16x16x32_bf16 v[0:3], v[176:179], v[208:211], v[0:3]
	v_mfma_f32_16x16x32_bf16 v[56:59], v[172:175], v[188:191], v[56:59]
	v_mfma_f32_16x16x32_bf16 v[48:51], v[180:183], v[188:191], v[48:51]
	v_mfma_f32_16x16x32_bf16 v[40:43], v[172:175], v[196:199], v[40:43]
	v_mfma_f32_16x16x32_bf16 v[32:35], v[180:183], v[196:199], v[32:35]
	v_mfma_f32_16x16x32_bf16 v[24:27], v[172:175], v[204:207], v[24:27]
	v_mfma_f32_16x16x32_bf16 v[16:19], v[180:183], v[204:207], v[16:19]
	v_mfma_f32_16x16x32_bf16 v[8:11], v[172:175], v[212:215], v[8:11]
	v_mfma_f32_16x16x32_bf16 v[0:3], v[180:183], v[212:215], v[0:3]
	s_barrier
	s_setprio 0
	s_add_u32 s28, s28, 0x100
	s_addc_u32 s29, s29, 0
	s_add_u32 s52, s52, 0x100
	s_addc_u32 s75, s75, 0
	s_cmp_ge_u32 s76, s54
	s_mov_b32 s30, s76
	s_cbranch_scc0 .LBB0_2452
	s_and_b64 vcc, exec, s[12:13]
	s_cbranch_vccz .LBB0_2455

; #define PG8_STAGE(bufoff, gbase, voff) do { _Pragma("unroll") for (int _i = 0; _i < 2; ++_i) \
;         __builtin_amdgcn_global_load_lds((const unsigned*)((const char*)(gbase) + (voff)[_i]), (LAS unsigned*)(lds + (bufoff) + ldsw + _i * 8192), 16, 0, 0); } while (0)
; #define PG8_LDA(dst, b, h) do { _Pragma("unroll") for (int m = 0; m < 4; ++m) _Pragma("unroll") for (int k = 0; k < 2; ++k) dst[m][k] = *(const LAS bf16x8*)(lds + PG8_SA(b, h) + aoff + m * 2048 + k * KOFF); } while (0)
; #define PG8_LDB(dst, b, h) do { _Pragma("unroll") for (int n = 0; n < 2; ++n) _Pragma("unroll") for (int k = 0; k < 2; ++k) dst[n][k] = *(const LAS bf16x8*)(lds + PG8_SB(b, h) + boff + n * 2048 + k * KOFF); } while (0)
; #define PG8_WAIT_V(n) asm volatile("s_waitcnt vmcnt(" #n ")" ::: "memory")
; #define PG8_WAIT_L(n) asm volatile("s_waitcnt lgkmcnt(" #n ")" ::: "memory")
; #define PG8_BAR __builtin_amdgcn_s_barrier()
; #define PG8_SCHED __builtin_amdgcn_sched_barrier(0)
; template <class Epi, bool ALIGN_EPI = true, bool FP8 = false>
; __device__ __forceinline__ void gemm_phase(LAS unsigned char* lds, const Gemm g, const StaticOrder& S, const Epi& E, const int wid) {
;     ...
;             const char* a1 = cA + (size_t)(t + 1) * kstep;
;             const char* a2 = last ? nA : cA + (size_t)(t + 2) * kstep; const char* b2 = last ? nB : cB + (size_t)(t + 2) * kstep;
;             const char* a3 = a2 + kstep; const char* b3 = b2 + kstep;
;             PG8_LDB(B0, 0, 0); PG8_LDB(B1, 0, 1); PG8_SCHED; PG8_LDA(At, 0, 0); PG8_STAGE(PG8_SA(1, 1), a1 + hstep, voffA);
;             PG8_WAIT_V(8); PG8_WAIT_L(0); PG8_BAR; PG8_MMA(0, 0, At, B0); PG8_MMA(0, 1, At, B1); PG8_BAR; PG8_SCHED;
;             PG8_LDA(At, 0, 1); PG8_STAGE(PG8_SB(0, 0), b2, voffB); PG8_STAGE(PG8_SB(0, 1), b2 + hstep, voffB); PG8_STAGE(PG8_SA(0, 0), a2, voffA);
;             PG8_WAIT_V(8); PG8_WAIT_L(0); PG8_BAR; PG8_MMA(1, 0, At, B0); PG8_MMA(1, 1, At, B1); PG8_BAR; PG8_SCHED;
.LBB0_2536:
	ds_read_b128 v[152:155], v188
	ds_read_b128 v[156:159], v188 offset:1024
	ds_read_b128 v[144:147], v188 offset:2048
	ds_read_b128 v[148:151], v188 offset:3072
	ds_read_b128 v[136:139], v189
	ds_read_b128 v[140:143], v189 offset:1024
	ds_read_b128 v[128:131], v189 offset:2048
	ds_read_b128 v[132:135], v189 offset:3072
	s_add_i32 s42, s26, 2
	s_add_u32 s27, s24, 0xfff50080
	s_addc_u32 s28, s25, -1
	s_cmp_eq_u32 s81, s26
	s_cselect_b32 s26, s20, s82
	s_cselect_b32 s29, s7, s28
	s_cselect_b32 s28, s6, s27
	s_cselect_b32 s27, s21, s83
	v_lshl_add_u64 v[216:217], s[24:25], 0, v[172:173]
	s_add_i32 m0, s34, 0xc000
	ds_read_b128 v[178:181], v190
	ds_read_b128 v[182:185], v190 offset:1024
	ds_read_b128 v[192:195], v190 offset:2048
	ds_read_b128 v[196:199], v190 offset:3072
	ds_read_b128 v[200:203], v190 offset:4096
	ds_read_b128 v[204:207], v190 offset:5120
	ds_read_b128 v[208:211], v190 offset:6144
	ds_read_b128 v[212:215], v190 offset:7168
	global_load_lds_dwordx4 v[216:217], off sc1
	v_lshl_add_u64 v[216:217], s[24:25], 0, v[174:175]
	s_add_i32 m0, s34, 0xe000
	s_nop 0
	global_load_lds_dwordx4 v[216:217], off sc1
	s_setprio 1
	s_waitcnt vmcnt(8) lgkmcnt(0)
	s_barrier
	v_mfma_f32_16x16x128_f8f6f4 v[120:123], v[152:159], v[178:185], v[120:123]
	v_mfma_f32_16x16x128_f8f6f4 v[124:127], v[144:151], v[178:185], v[124:127]
	v_mfma_f32_16x16x128_f8f6f4 v[112:115], v[152:159], v[192:199], v[112:115]
	v_mfma_f32_16x16x128_f8f6f4 v[116:119], v[144:151], v[192:199], v[116:119]
	v_mfma_f32_16x16x128_f8f6f4 v[96:99], v[152:159], v[200:207], v[96:99]
	v_mfma_f32_16x16x128_f8f6f4 v[100:103], v[144:151], v[200:207], v[100:103]
	v_mfma_f32_16x16x128_f8f6f4 v[80:83], v[152:159], v[208:215], v[80:83]
	v_mfma_f32_16x16x128_f8f6f4 v[84:87], v[144:151], v[208:215], v[84:87]
	v_mfma_f32_16x16x128_f8f6f4 v[104:107], v[136:143], v[178:185], v[104:107]
	v_mfma_f32_16x16x128_f8f6f4 v[108:111], v[128:135], v[178:185], v[108:111]
	v_mfma_f32_16x16x128_f8f6f4 v[88:91], v[136:143], v[192:199], v[88:91]
	v_mfma_f32_16x16x128_f8f6f4 v[92:95], v[128:135], v[192:199], v[92:95]
	v_mfma_f32_16x16x128_f8f6f4 v[72:75], v[136:143], v[200:207], v[72:75]
	v_mfma_f32_16x16x128_f8f6f4 v[76:79], v[128:135], v[200:207], v[76:79]
	v_mfma_f32_16x16x128_f8f6f4 v[64:67], v[136:143], v[208:215], v[64:67]
	v_mfma_f32_16x16x128_f8f6f4 v[68:71], v[128:135], v[208:215], v[68:71]
	s_barrier
	s_setprio 0
	s_add_i32 s43, s64, s31
	v_lshl_add_u64 v[178:179], s[26:27], 0, v[162:163]
	s_mov_b32 m0, s43
	ds_read_b128 v[192:195], v190 offset:16384
	ds_read_b128 v[196:199], v190 offset:17408
	ds_read_b128 v[200:203], v190 offset:18432
	ds_read_b128 v[204:207], v190 offset:19456
	ds_read_b128 v[208:211], v190 offset:20480
	ds_read_b128 v[212:215], v190 offset:21504
	ds_read_b128 v[216:219], v190 offset:22528
	ds_read_b128 v[220:223], v190 offset:23552
	global_load_lds_dwordx4 v[178:179], off sc1
	s_add_i32 m0, s43, 0x2000
	s_add_u32 s84, s26, 0xb0000
	v_lshl_add_u64 v[180:181], s[26:27], 0, v[166:167]
	s_addc_u32 s85, s27, 0
	s_add_i32 s43, s65, s31
	global_load_lds_dwordx4 v[180:181], off sc1
	v_lshl_add_u64 v[182:183], s[84:85], 0, v[162:163]
	s_mov_b32 m0, s43
	v_lshl_add_u64 v[184:185], s[28:29], 0, v[164:165]
	global_load_lds_dwordx4 v[182:183], off sc1
	v_lshl_add_u64 v[182:183], s[84:85], 0, v[166:167]
	s_add_i32 m0, s43, 0x2000
	s_nop 0
	global_load_lds_dwordx4 v[182:183], off sc1
	v_lshl_add_u64 v[182:183], s[28:29], 0, v[160:161]
	s_mov_b32 m0, s34
	s_nop 0
	global_load_lds_dwordx4 v[182:183], off sc1
	s_mov_b32 m0, s35
	s_nop 0
	global_load_lds_dwordx4 v[184:185], off sc1
	s_setprio 1
	s_waitcnt vmcnt(8) lgkmcnt(0)
	s_barrier
	v_mfma_f32_16x16x128_f8f6f4 v[56:59], v[152:159], v[192:199], v[56:59]
	v_mfma_f32_16x16x128_f8f6f4 v[60:63], v[144:151], v[192:199], v[60:63]
	v_mfma_f32_16x16x128_f8f6f4 v[48:51], v[152:159], v[200:207], v[48:51]
	v_mfma_f32_16x16x128_f8f6f4 v[52:55], v[144:151], v[200:207], v[52:55]
	v_mfma_f32_16x16x128_f8f6f4 v[32:35], v[152:159], v[208:215], v[32:35]
	v_mfma_f32_16x16x128_f8f6f4 v[224:227], v[144:151], v[208:215], v[36:39]
	v_mfma_f32_16x16x128_f8f6f4 v[228:231], v[152:159], v[216:223], v[16:19]
	v_mfma_f32_16x16x128_f8f6f4 v[232:235], v[144:151], v[216:223], v[20:23]
	v_mfma_f32_16x16x128_f8f6f4 v[44:47], v[128:135], v[192:199], v[44:47]
	v_mfma_f32_16x16x128_f8f6f4 v[236:239], v[136:143], v[192:199], v[40:43]
	v_mfma_f32_16x16x128_f8f6f4 v[240:243], v[136:143], v[200:207], v[24:27]
	v_mfma_f32_16x16x128_f8f6f4 v[200:203], v[128:135], v[200:207], v[28:31]
	v_mfma_f32_16x16x128_f8f6f4 v[204:207], v[136:143], v[208:215], v[8:11]
	v_mfma_f32_16x16x128_f8f6f4 v[208:211], v[128:135], v[208:215], v[12:15]
	v_mfma_f32_16x16x128_f8f6f4 v[212:215], v[136:143], v[216:223], v[0:3]
	v_mfma_f32_16x16x128_f8f6f4 v[216:219], v[128:135], v[216:223], v[4:7]
	s_barrier
; #define PG8_STAGE(bufoff, gbase, voff) do { _Pragma("unroll") for (int _i = 0; _i < 2; ++_i) \
;         __builtin_amdgcn_global_load_lds((const unsigned*)((const char*)(gbase) + (voff)[_i]), (LAS unsigned*)(lds + (bufoff) + ldsw + _i * 8192), 16, 0, 0); } while (0)
; #define PG8_LDA(dst, b, h) do { _Pragma("unroll") for (int m = 0; m < 4; ++m) _Pragma("unroll") for (int k = 0; k < 2; ++k) dst[m][k] = *(const LAS bf16x8*)(lds + PG8_SA(b, h) + aoff + m * 2048 + k * KOFF); } while (0)
; #define PG8_LDB(dst, b, h) do { _Pragma("unroll") for (int n = 0; n < 2; ++n) _Pragma("unroll") for (int k = 0; k < 2; ++k) dst[n][k] = *(const LAS bf16x8*)(lds + PG8_SB(b, h) + boff + n * 2048 + k * KOFF); } while (0)
; #define PG8_WAIT_V(n) asm volatile("s_waitcnt vmcnt(" #n ")" ::: "memory")
; #define PG8_WAIT_L(n) asm volatile("s_waitcnt lgkmcnt(" #n ")" ::: "memory")
; #define PG8_BAR __builtin_amdgcn_s_barrier()
; #define PG8_SCHED __builtin_amdgcn_sched_barrier(0)
; template <class Epi, bool ALIGN_EPI = true, bool FP8 = false>
; __device__ __forceinline__ void gemm_phase(LAS unsigned char* lds, const Gemm g, const StaticOrder& S, const Epi& E, const int wid) {
;     ...
;             PG8_WAIT_V(8); PG8_WAIT_L(0); PG8_BAR; PG8_MMA(1, 0, At, B0); PG8_MMA(1, 1, At, B1); PG8_BAR; PG8_SCHED;
;             PG8_LDB(B0, 1, 0); PG8_LDB(B1, 1, 1); PG8_SCHED; PG8_LDA(At, 1, 0); PG8_STAGE(PG8_SA(0, 1), a2 + hstep, voffA);
;             PG8_WAIT_V(8); PG8_WAIT_L(0); PG8_BAR; PG8_MMA(0, 0, At, B0); PG8_MMA(0, 1, At, B1); PG8_BAR; PG8_SCHED;
;             PG8_LDA(At, 1, 1); PG8_STAGE(PG8_SB(1, 0), b3, voffB); PG8_STAGE(PG8_SB(1, 1), b3 + hstep, voffB); PG8_STAGE(PG8_SA(1, 0), a3, voffA);
;             PG8_WAIT_V(8); PG8_WAIT_L(0); PG8_BAR; PG8_MMA(1, 0, At, B0); PG8_MMA(1, 1, At, B1); PG8_BAR; PG8_SCHED;
;         }
	s_setprio 0
	s_add_i32 s43, 0, 0x18000
	s_add_i32 s54, 0, 0x1c000
	s_nop 0
	v_add_u32_e32 v12, s43, v187
	v_add_u32_e32 v16, s54, v187
	ds_read_b128 v[0:3], v12
	ds_read_b128 v[4:7], v12 offset:1024
	ds_read_b128 v[8:11], v12 offset:2048
	ds_read_b128 v[12:15], v12 offset:3072
	ds_read_b128 v[128:131], v16
	ds_read_b128 v[132:135], v16 offset:1024
	ds_read_b128 v[136:139], v16 offset:2048
	ds_read_b128 v[140:143], v16 offset:3072
	s_add_u32 s28, s28, 0xb0000
	s_addc_u32 s29, s29, 0
	s_mov_b32 m0, s36
	v_lshl_add_u64 v[152:153], s[28:29], 0, v[160:161]
	ds_read_b128 v[16:19], v190 offset:32768
	ds_read_b128 v[20:23], v190 offset:33792
	ds_read_b128 v[24:27], v190 offset:34816
	ds_read_b128 v[28:31], v190 offset:35840
	ds_read_b128 v[36:39], v190 offset:36864
	ds_read_b128 v[40:43], v190 offset:37888
	ds_read_b128 v[144:147], v190 offset:38912
	ds_read_b128 v[148:151], v190 offset:39936
	global_load_lds_dwordx4 v[152:153], off sc1
	v_lshl_add_u64 v[152:153], s[28:29], 0, v[164:165]
	s_mov_b32 m0, s37
	s_nop 0
	global_load_lds_dwordx4 v[152:153], off sc1
	s_setprio 1
	s_waitcnt vmcnt(8) lgkmcnt(0)
	s_barrier
	v_mfma_f32_16x16x128_f8f6f4 v[120:123], v[0:7], v[16:23], v[120:123]
	v_mfma_f32_16x16x128_f8f6f4 v[124:127], v[8:15], v[16:23], v[124:127]
	v_mfma_f32_16x16x128_f8f6f4 v[112:115], v[0:7], v[24:31], v[112:115]
	v_mfma_f32_16x16x128_f8f6f4 v[116:119], v[8:15], v[24:31], v[116:119]
	v_mfma_f32_16x16x128_f8f6f4 v[96:99], v[0:7], v[36:43], v[96:99]
	v_mfma_f32_16x16x128_f8f6f4 v[100:103], v[8:15], v[36:43], v[100:103]
	v_mfma_f32_16x16x128_f8f6f4 v[80:83], v[0:7], v[144:151], v[80:83]
	v_mfma_f32_16x16x128_f8f6f4 v[84:87], v[8:15], v[144:151], v[84:87]
	v_mfma_f32_16x16x128_f8f6f4 v[104:107], v[128:135], v[16:23], v[104:107]
	v_mfma_f32_16x16x128_f8f6f4 v[108:111], v[136:143], v[16:23], v[108:111]
	v_mfma_f32_16x16x128_f8f6f4 v[88:91], v[128:135], v[24:31], v[88:91]
	v_mfma_f32_16x16x128_f8f6f4 v[92:95], v[136:143], v[24:31], v[92:95]
	v_mfma_f32_16x16x128_f8f6f4 v[72:75], v[128:135], v[36:43], v[72:75]
	v_mfma_f32_16x16x128_f8f6f4 v[76:79], v[136:143], v[36:43], v[76:79]
	v_mfma_f32_16x16x128_f8f6f4 v[64:67], v[128:135], v[144:151], v[64:67]
	v_mfma_f32_16x16x128_f8f6f4 v[68:71], v[136:143], v[144:151], v[68:71]
	s_barrier
	s_setprio 0
	s_add_i32 s28, s43, s31
	v_lshl_add_u64 v[16:17], v[178:179], 0, s[14:15]
	s_mov_b32 m0, s28
	ds_read_b128 v[24:27], v190 offset:49152
	ds_read_b128 v[28:31], v190 offset:50176
	ds_read_b128 v[144:147], v190 offset:51200
	ds_read_b128 v[148:151], v190 offset:52224
	ds_read_b128 v[152:155], v190 offset:53248
	ds_read_b128 v[156:159], v190 offset:54272
	ds_read_b128 v[192:195], v190 offset:55296
	ds_read_b128 v[196:199], v190 offset:56320
	global_load_lds_dwordx4 v[16:17], off sc1
	s_add_i32 m0, s28, 0x2000
	s_add_u32 s26, s26, 0xb0080
	v_lshl_add_u64 v[16:17], v[180:181], 0, s[14:15]
	s_addc_u32 s27, s27, 0
	s_add_i32 s28, s54, s31
	global_load_lds_dwordx4 v[16:17], off sc1
	v_lshl_add_u64 v[16:17], s[26:27], 0, v[162:163]
	s_mov_b32 m0, s28
	s_nop 0
	global_load_lds_dwordx4 v[16:17], off sc1
	v_lshl_add_u64 v[16:17], s[26:27], 0, v[166:167]
	s_add_i32 m0, s28, 0x2000
	s_nop 0
	global_load_lds_dwordx4 v[16:17], off sc1
	v_lshl_add_u64 v[16:17], v[182:183], 0, s[14:15]
	s_mov_b32 m0, s52
	s_nop 0
	global_load_lds_dwordx4 v[16:17], off sc1
	v_lshl_add_u64 v[16:17], v[184:185], 0, s[14:15]
	s_mov_b32 m0, s53
	s_nop 0
	global_load_lds_dwordx4 v[16:17], off sc1
	s_setprio 1
	s_waitcnt vmcnt(8) lgkmcnt(0)
	s_barrier
	v_mfma_f32_16x16x128_f8f6f4 v[56:59], v[0:7], v[24:31], v[56:59]
	v_mfma_f32_16x16x128_f8f6f4 v[60:63], v[8:15], v[24:31], v[60:63]
	v_mfma_f32_16x16x128_f8f6f4 v[48:51], v[0:7], v[144:151], v[48:51]
	v_mfma_f32_16x16x128_f8f6f4 v[52:55], v[8:15], v[144:151], v[52:55]
	v_mfma_f32_16x16x128_f8f6f4 v[32:35], v[0:7], v[152:159], v[32:35]
	v_mfma_f32_16x16x128_f8f6f4 v[36:39], v[8:15], v[152:159], v[224:227]
	v_mfma_f32_16x16x128_f8f6f4 v[16:19], v[0:7], v[192:199], v[228:231]
	v_mfma_f32_16x16x128_f8f6f4 v[20:23], v[8:15], v[192:199], v[232:235]
	v_mfma_f32_16x16x128_f8f6f4 v[40:43], v[128:135], v[24:31], v[236:239]
	v_mfma_f32_16x16x128_f8f6f4 v[44:47], v[136:143], v[24:31], v[44:47]
	v_mfma_f32_16x16x128_f8f6f4 v[24:27], v[128:135], v[144:151], v[240:243]
	v_mfma_f32_16x16x128_f8f6f4 v[28:31], v[136:143], v[144:151], v[200:203]
	v_mfma_f32_16x16x128_f8f6f4 v[8:11], v[128:135], v[152:159], v[204:207]
	v_mfma_f32_16x16x128_f8f6f4 v[12:15], v[136:143], v[152:159], v[208:211]
	v_mfma_f32_16x16x128_f8f6f4 v[0:3], v[128:135], v[192:199], v[212:215]
	v_mfma_f32_16x16x128_f8f6f4 v[4:7], v[136:143], v[192:199], v[216:219]
	s_barrier
	s_setprio 0
	s_add_u32 s24, s24, 0x100
	s_addc_u32 s25, s25, 0
	s_add_u32 s82, s82, 0x100
	s_addc_u32 s83, s83, 0
	s_cmp_ge_u32 s42, s80
	s_mov_b32 s26, s42
	s_cbranch_scc0 .LBB0_2536
	s_and_b64 vcc, exec, s[16:17]
	s_cbranch_vccz .LBB0_2539
	s_barrier
